# sample attention K/V cache row loads marked nt (read once); plus removal of 80 redundant s_nop after cvt in the prompt attention loops
# speedup vs baseline: 1.0800x; 1.0227x over previous
.LBB0_1114:
	s_mov_b64 s[68:69], 0
	s_and_b64 vcc, exec, s[0:1]
	s_mov_b64 s[0:1], 0
	s_cbranch_vccz .LBB0_1243
	s_add_i32 s0, s63, 0xfffffde0
	s_lshr_b32 s60, s0, 3
	s_lshl_b32 s92, s60, 14
	v_readlane_b32 s12, v254, 29
	s_and_b32 s10, s63, 7
	s_add_i32 s10, s10, s60
	s_and_b32 s10, s10, 7
	s_lshl_b64 s[0:1], s[92:93], 2
	v_readlane_b32 s20, v254, 37
	v_mov_b32_e32 v105, v0
	v_readlane_b32 s21, v254, 38
	s_add_u32 s0, s20, s0
	s_addc_u32 s1, s21, s1
	s_lshl_b32 s2, s10, 2
	v_lshlrev_b32_e32 v2, 2, v105
	s_add_u32 s0, s0, s2
	v_ashrrev_i32_e32 v3, 31, v2
	s_addc_u32 s1, s1, 0
	v_lshlrev_b64 v[4:5], 5, v[2:3]
	v_lshl_add_u64 v[4:5], s[0:1], 0, v[4:5]
	global_load_dword v6, v[4:5], off
	v_or_b32_e32 v4, 1, v2
	v_ashrrev_i32_e32 v5, 31, v4
	v_lshlrev_b64 v[4:5], 5, v[4:5]
	v_lshl_add_u64 v[4:5], s[0:1], 0, v[4:5]
	global_load_dword v7, v[4:5], off
	v_or_b32_e32 v4, 2, v2
	v_ashrrev_i32_e32 v5, 31, v4
	v_or_b32_e32 v2, 3, v2
	v_lshlrev_b64 v[4:5], 5, v[4:5]
	v_ashrrev_i32_e32 v3, 31, v2
	v_lshl_add_u64 v[4:5], s[0:1], 0, v[4:5]
	v_lshlrev_b64 v[2:3], 5, v[2:3]
	global_load_dword v8, v[4:5], off
	v_lshl_add_u64 v[2:3], s[0:1], 0, v[2:3]
	global_load_dword v3, v[2:3], off
	s_add_i32 s34, s63, 0xfffffde0
	s_lshr_b32 s70, s34, 3
	s_and_b32 s71, s34, 7
	s_add_i32 s71, s71, s70
	s_and_b32 s71, s71, 7
	v_lshrrev_b32_e32 v80, 6, v0
	v_and_b32_e32 v77, 15, v0
	v_bfe_u32 v76, v0, 4, 2
	v_readfirstlane_b32 s72, v80
	v_readlane_b32 s34, v254, 33
	v_readlane_b32 s35, v254, 34
	v_readlane_b32 s36, v254, 35
	v_readlane_b32 s37, v254, 36
	v_lshlrev_b32_e32 v72, 11, v76
	v_lshl_add_u32 v72, v77, 4, v72
	v_add_u32_e32 v73, 0x2000, v72
	v_add_u32_e32 v74, 0x4000, v72
	v_add_u32_e32 v75, 0x6000, v72
	v_lshlrev_b32_e32 v81, 10, v77
	v_lshl_add_u32 v81, v76, 4, v81
	s_lshl_b32 s38, s70, 22
	s_lshl_b32 s39, s71, 8
	s_add_i32 s38, s38, s39
	s_lshl_b32 s39, s72, 15
	s_add_i32 s38, s38, s39
	s_add_u32 s74, s34, s38
	s_addc_u32 s75, s35, 0
	s_add_u32 s76, s36, s38
	s_addc_u32 s77, s37, 0
	s_add_u32 s78, s76, 0x40000
	s_addc_u32 s79, s77, 0
	s_lshl_b32 s38, s70, 14
	s_lshl_b32 s39, s71, 7
	s_add_i32 s38, s38, s39
	s_add_i32 s39, s38, 0x7faea00
	s_add_u32 s80, s90, s39
	s_addc_u32 s81, s91, 0
	s_add_i32 s39, s38, 0x1e2ea00
	s_add_u32 s86, s90, s39
	s_addc_u32 s87, s91, 0
	s_lshl_b32 s38, s70, 15
	s_lshl_b32 s39, s71, 8
	s_add_i32 s38, s38, s39
	s_add_i32 s39, s38, 0x821c000
	s_add_u32 s82, s88, s39
	s_addc_u32 s83, s89, 0
	s_add_i32 s39, s38, 0x829c000
	s_add_u32 s84, s88, s39
	s_addc_u32 s85, s89, 0
	s_lshl_b32 s73, s72, 13
	s_add_i32 s73, s73, 0xd400
	global_load_dwordx4 v[64:67], v81, s[80:81]
	global_load_dwordx4 v[68:71], v81, s[80:81] offset:64
	s_cmp_lg_u32 s72, 0
	s_cbranch_scc1 .Lsa_pre_nz
	global_load_dwordx4 v[232:235], v72, s[82:83] nt
	global_load_dwordx4 v[236:239], v73, s[82:83] nt
	global_load_dwordx4 v[240:243], v74, s[82:83] nt
	global_load_dwordx4 v[244:247], v75, s[82:83] nt
.Lsa_pre_nz:
	global_load_dwordx4 v[16:19], v72, s[74:75] nt
	global_load_dwordx4 v[20:23], v73, s[74:75] nt
	global_load_dwordx4 v[24:27], v74, s[74:75] nt
	global_load_dwordx4 v[28:31], v75, s[74:75] nt
	s_add_u32 s74, s74, 0x40000
	s_addc_u32 s75, s75, 0
	global_load_dwordx4 v[32:35], v72, s[74:75] nt
	global_load_dwordx4 v[36:39], v73, s[74:75] nt
	global_load_dwordx4 v[40:43], v74, s[74:75] nt
	global_load_dwordx4 v[44:47], v75, s[74:75] nt
	s_add_u32 s74, s74, 0x40000
	s_addc_u32 s75, s75, 0
	global_load_dwordx4 v[48:51], v72, s[74:75] nt
	global_load_dwordx4 v[52:55], v73, s[74:75] nt
	global_load_dwordx4 v[56:59], v74, s[74:75] nt
	global_load_dwordx4 v[60:63], v75, s[74:75] nt
	s_add_u32 s74, s74, 0x40000
	s_addc_u32 s75, s75, 0
	global_load_dwordx4 v[180:183], v72, s[74:75] nt
	global_load_dwordx4 v[184:187], v73, s[74:75] nt
	global_load_dwordx4 v[188:191], v74, s[74:75] nt
	global_load_dwordx4 v[192:195], v75, s[74:75] nt
	s_add_u32 s74, s74, 0x40000
	s_addc_u32 s75, s75, 0
	global_load_dwordx4 v[200:203], v72, s[74:75] nt
	global_load_dwordx4 v[204:207], v73, s[74:75] nt
	global_load_dwordx4 v[208:211], v74, s[74:75] nt
	global_load_dwordx4 v[212:215], v75, s[74:75] nt
	s_add_u32 s74, s74, 0x40000
	s_addc_u32 s75, s75, 0
	v_cmp_lt_i32_e32 vcc, v87, v84
	v_cmp_lt_i32_e64 s[0:1], v88, v84
	v_and_b32_e32 v106, 63, v105
	v_cndmask_b32_e32 v2, v87, v83, vcc
	v_lshlrev_b32_e32 v9, 2, v2
	v_cmp_eq_u32_e32 vcc, 0, v106
	v_cmp_gt_u32_e64 s[28:29], 16, v106
	v_ashrrev_i32_e32 v107, 6, v105
	v_readlane_b32 s13, v254, 30
	v_readlane_b32 s14, v254, 31
	v_readlane_b32 s15, v254, 32
	v_readlane_b32 s16, v254, 33
	v_readlane_b32 s17, v254, 34
	v_readlane_b32 s18, v254, 35
	v_readlane_b32 s19, v254, 36
	v_readlane_b32 s22, v254, 39
	v_readlane_b32 s23, v254, 40
	v_readlane_b32 s24, v254, 41
	v_readlane_b32 s25, v254, 42
	v_readlane_b32 s26, v254, 43
	v_readlane_b32 s27, v254, 44
	s_waitcnt vmcnt(25)
	v_add_f32_e32 v4, 0, v6
	s_waitcnt vmcnt(24)
	v_add_f32_e32 v5, v4, v7
	v_cndmask_b32_e64 v7, v88, v83, s[0:1]
	v_lshlrev_b32_e32 v7, 2, v7
	s_waitcnt vmcnt(23)
	v_add_f32_e32 v2, v5, v8
	s_waitcnt vmcnt(22)
	v_add_f32_e32 v3, v2, v3
	ds_bpermute_b32 v6, v9, v3
	s_waitcnt lgkmcnt(0)
	v_add_f32_e32 v6, v3, v6
	v_cndmask_b32_e32 v6, v6, v3, vcc
	ds_bpermute_b32 v7, v7, v6
	v_cmp_lt_i32_e32 vcc, v89, v84
	s_waitcnt lgkmcnt(0)
	v_add_f32_e32 v7, v6, v7
	v_cndmask_b32_e32 v8, v89, v83, vcc
	v_cmp_gt_u32_e32 vcc, 2, v106
	v_lshlrev_b32_e32 v8, 2, v8
	s_nop 0
	v_cndmask_b32_e32 v6, v7, v6, vcc
	ds_bpermute_b32 v7, v8, v6
	v_cmp_lt_i32_e32 vcc, v90, v84
	s_waitcnt lgkmcnt(0)
	v_add_f32_e32 v7, v6, v7
	v_cndmask_b32_e32 v8, v90, v83, vcc
	v_cmp_gt_u32_e32 vcc, 4, v106
	v_lshlrev_b32_e32 v8, 2, v8
	s_nop 0
	v_cndmask_b32_e32 v6, v7, v6, vcc
	ds_bpermute_b32 v7, v8, v6
	v_cmp_lt_i32_e32 vcc, v91, v84
	s_waitcnt lgkmcnt(0)
	v_add_f32_e32 v7, v6, v7
	v_cndmask_b32_e32 v8, v91, v83, vcc
	v_cmp_gt_u32_e32 vcc, 8, v106
	v_lshlrev_b32_e32 v8, 2, v8
	s_nop 0
	v_cndmask_b32_e32 v6, v7, v6, vcc
	ds_bpermute_b32 v7, v8, v6
	v_cmp_lt_i32_e32 vcc, v92, v84
	s_waitcnt lgkmcnt(0)
	v_add_f32_e32 v7, v6, v7
	v_cndmask_b32_e32 v8, v92, v83, vcc
	v_lshlrev_b32_e32 v8, 2, v8
	v_cndmask_b32_e64 v6, v7, v6, s[28:29]
	ds_bpermute_b32 v7, v8, v6
	v_cmp_eq_u32_e32 vcc, 63, v106
	s_waitcnt lgkmcnt(0)
	v_add_f32_e32 v7, v6, v7
	s_and_saveexec_b64 s[0:1], vcc
	v_lshl_add_u32 v8, v107, 2, 16
	ds_write_b32 v8, v7 offset:8448
	s_or_b64 exec, exec, s[0:1]
	v_cmp_gt_u32_e32 vcc, 32, v106
	s_waitcnt lgkmcnt(0)
	s_barrier
	v_cndmask_b32_e32 v6, v7, v6, vcc
	v_sub_f32_e32 v6, v6, v3
	v_cmp_lt_i32_e32 vcc, 0, v107
	s_and_saveexec_b64 s[0:1], vcc
	s_cbranch_execz .LBB0_1127
	v_add_u32_e32 v7, -1, v107
	v_cmp_lt_u32_e32 vcc, 6, v7
	v_mov_b32_e32 v7, 0
	s_and_saveexec_b64 s[2:3], vcc
	s_cbranch_execz .LBB0_1122
	v_and_b32_e32 v7, 0x7ffffff8, v107
	s_mov_b32 s4, 0
	s_mov_b64 s[6:7], 0
	v_readlane_b32 s5, v255, 0

.LBB0_1129:
	s_or_b64 exec, exec, s[0:1]
	s_waitcnt lgkmcnt(0)
	s_barrier
	v_lshlrev_b32_e32 v80, 4, v76
	s_lshl_b32 s0, s72, 6
	s_add_i32 s0, s0, 16
	v_add_u32_e32 v80, s0, v80
	v_lshlrev_b32_e32 v81, 2, v0
	v_xor_b32_e32 v15, v77, v76
	v_lshlrev_b32_e32 v15, 4, v15
	v_lshl_add_u32 v15, v76, 8, v15
	v_add_u32_e32 v105, s73, v15
	v_xor_b32_e32 v106, 0x40, v15
	v_add_u32_e32 v106, 0x400, v106
	v_add_u32_e32 v106, s73, v106
	v_xor_b32_e32 v107, 0x80, v15
	v_add_u32_e32 v107, 0x800, v107
	v_add_u32_e32 v107, s73, v107
	v_xor_b32_e32 v108, 0xc0, v15
	v_add_u32_e32 v108, 0xc00, v108
	v_add_u32_e32 v108, s73, v108
	v_lshlrev_b32_e32 v15, 1, v76
	v_xor_b32_e32 v15, v15, v77
	v_lshlrev_b32_e32 v15, 4, v15
	v_lshl_add_u32 v15, v77, 8, v15
	v_add_u32_e32 v109, s73, v15
	v_xor_b32_e32 v110, 0x10, v15
	v_add_u32_e32 v110, s73, v110
	v_xor_b32_e32 v111, 0x80, v15
	v_add_u32_e32 v111, s73, v111
	v_xor_b32_e32 v14, 0x90, v15
	v_add_u32_e32 v14, s73, v14
	v_mov_b32_e32 v176, v101
	v_mov_b32_e32 v177, v101
	v_mov_b32_e32 v178, v101
	v_mov_b32_e32 v179, v101
	s_waitcnt vmcnt(16)
	ds_write_b128 v105, v[16:19]
	ds_write_b128 v106, v[20:23]
	ds_write_b128 v107, v[24:27]
	ds_write_b128 v108, v[28:31]
	global_load_dwordx4 v[16:19], v72, s[74:75] nt
	global_load_dwordx4 v[20:23], v73, s[74:75] nt
	global_load_dwordx4 v[24:27], v74, s[74:75] nt
	global_load_dwordx4 v[28:31], v75, s[74:75] nt
	s_add_u32 s74, s74, 0x40000
	s_addc_u32 s75, s75, 0
	ds_read_b128 v[216:219], v109
	ds_read_b128 v[220:223], v110
	ds_read_b128 v[224:227], v111
	ds_read_b128 v[228:231], v14
	ds_read_b128 v[112:115], v80
	s_waitcnt lgkmcnt(0)
	v_cvt_pk_bf16_f32 v2, v216, v217
	v_cvt_pk_bf16_f32 v3, v218, v219
	v_cvt_pk_bf16_f32 v4, v220, v221
	v_cvt_pk_bf16_f32 v5, v222, v223
	v_cvt_pk_bf16_f32 v6, v224, v225
	v_cvt_pk_bf16_f32 v7, v226, v227
	v_cvt_pk_bf16_f32 v8, v228, v229
	v_cvt_pk_bf16_f32 v9, v230, v231
	s_nop 0
	v_mfma_f32_16x16x32_bf16 v[112:115], v[2:5], v[64:67], v[112:115]
	v_mfma_f32_16x16x32_bf16 v[112:115], v[6:9], v[68:71], v[112:115]
	s_waitcnt vmcnt(16)
	ds_write_b128 v105, v[32:35]
	ds_write_b128 v106, v[36:39]
	ds_write_b128 v107, v[40:43]
	ds_write_b128 v108, v[44:47]
	global_load_dwordx4 v[32:35], v72, s[74:75] nt
	global_load_dwordx4 v[36:39], v73, s[74:75] nt
	global_load_dwordx4 v[40:43], v74, s[74:75] nt
	global_load_dwordx4 v[44:47], v75, s[74:75] nt
	s_add_u32 s74, s74, 0x40000
	s_addc_u32 s75, s75, 0
	ds_read_b128 v[216:219], v109
	ds_read_b128 v[220:223], v110
	ds_read_b128 v[224:227], v111
	ds_read_b128 v[228:231], v14
	ds_read_b128 v[116:119], v80 offset:512
	s_waitcnt lgkmcnt(0)
	v_cvt_pk_bf16_f32 v2, v216, v217
	v_cvt_pk_bf16_f32 v3, v218, v219
	v_cvt_pk_bf16_f32 v4, v220, v221
	v_cvt_pk_bf16_f32 v5, v222, v223
	v_cvt_pk_bf16_f32 v6, v224, v225
	v_cvt_pk_bf16_f32 v7, v226, v227
	v_cvt_pk_bf16_f32 v8, v228, v229
	v_cvt_pk_bf16_f32 v9, v230, v231
	s_nop 0
	v_mfma_f32_16x16x32_bf16 v[116:119], v[2:5], v[64:67], v[116:119]
	v_mfma_f32_16x16x32_bf16 v[116:119], v[6:9], v[68:71], v[116:119]
	s_waitcnt vmcnt(16)
	ds_write_b128 v105, v[48:51]
	ds_write_b128 v106, v[52:55]
	ds_write_b128 v107, v[56:59]
	ds_write_b128 v108, v[60:63]
	global_load_dwordx4 v[48:51], v72, s[74:75] nt
	global_load_dwordx4 v[52:55], v73, s[74:75] nt
	global_load_dwordx4 v[56:59], v74, s[74:75] nt
	global_load_dwordx4 v[60:63], v75, s[74:75] nt
	s_add_u32 s74, s74, 0x40000
	s_addc_u32 s75, s75, 0
	ds_read_b128 v[216:219], v109
	ds_read_b128 v[220:223], v110
	ds_read_b128 v[224:227], v111
	ds_read_b128 v[228:231], v14
	ds_read_b128 v[120:123], v80 offset:1024
	s_waitcnt lgkmcnt(0)
	v_cvt_pk_bf16_f32 v2, v216, v217
	v_cvt_pk_bf16_f32 v3, v218, v219
	v_cvt_pk_bf16_f32 v4, v220, v221
	v_cvt_pk_bf16_f32 v5, v222, v223
	v_cvt_pk_bf16_f32 v6, v224, v225
	v_cvt_pk_bf16_f32 v7, v226, v227
	v_cvt_pk_bf16_f32 v8, v228, v229
	v_cvt_pk_bf16_f32 v9, v230, v231
	s_nop 0
	v_mfma_f32_16x16x32_bf16 v[120:123], v[2:5], v[64:67], v[120:123]
	v_mfma_f32_16x16x32_bf16 v[120:123], v[6:9], v[68:71], v[120:123]
	s_waitcnt vmcnt(16)
	ds_write_b128 v105, v[180:183]
	ds_write_b128 v106, v[184:187]
	ds_write_b128 v107, v[188:191]
	ds_write_b128 v108, v[192:195]
	global_load_dwordx4 v[180:183], v72, s[74:75] nt
	global_load_dwordx4 v[184:187], v73, s[74:75] nt
	global_load_dwordx4 v[188:191], v74, s[74:75] nt
	global_load_dwordx4 v[192:195], v75, s[74:75] nt
	s_add_u32 s74, s74, 0x40000
	s_addc_u32 s75, s75, 0
	ds_read_b128 v[216:219], v109
	ds_read_b128 v[220:223], v110
	ds_read_b128 v[224:227], v111
	ds_read_b128 v[228:231], v14
	ds_read_b128 v[124:127], v80 offset:1536
	s_waitcnt lgkmcnt(0)
	v_cvt_pk_bf16_f32 v2, v216, v217
	v_cvt_pk_bf16_f32 v3, v218, v219
	v_cvt_pk_bf16_f32 v4, v220, v221
	v_cvt_pk_bf16_f32 v5, v222, v223
	v_cvt_pk_bf16_f32 v6, v224, v225
	v_cvt_pk_bf16_f32 v7, v226, v227
	v_cvt_pk_bf16_f32 v8, v228, v229
	v_cvt_pk_bf16_f32 v9, v230, v231
	s_nop 0
	v_mfma_f32_16x16x32_bf16 v[124:127], v[2:5], v[64:67], v[124:127]
	v_mfma_f32_16x16x32_bf16 v[124:127], v[6:9], v[68:71], v[124:127]
	s_waitcnt vmcnt(16)
	ds_write_b128 v105, v[200:203]
	ds_write_b128 v106, v[204:207]
	ds_write_b128 v107, v[208:211]
	ds_write_b128 v108, v[212:215]
	global_load_dwordx4 v[200:203], v72, s[74:75] nt
	global_load_dwordx4 v[204:207], v73, s[74:75] nt
	global_load_dwordx4 v[208:211], v74, s[74:75] nt
	global_load_dwordx4 v[212:215], v75, s[74:75] nt
	s_add_u32 s74, s74, 0x40000
	s_addc_u32 s75, s75, 0
	ds_read_b128 v[216:219], v109
	ds_read_b128 v[220:223], v110
	ds_read_b128 v[224:227], v111
	ds_read_b128 v[228:231], v14
	ds_read_b128 v[128:131], v80 offset:2048
	s_waitcnt lgkmcnt(0)
	v_cvt_pk_bf16_f32 v2, v216, v217
	v_cvt_pk_bf16_f32 v3, v218, v219
	v_cvt_pk_bf16_f32 v4, v220, v221
	v_cvt_pk_bf16_f32 v5, v222, v223
	v_cvt_pk_bf16_f32 v6, v224, v225
	v_cvt_pk_bf16_f32 v7, v226, v227
	v_cvt_pk_bf16_f32 v8, v228, v229
	v_cvt_pk_bf16_f32 v9, v230, v231
	s_nop 0
	v_mfma_f32_16x16x32_bf16 v[128:131], v[2:5], v[64:67], v[128:131]
	v_mfma_f32_16x16x32_bf16 v[128:131], v[6:9], v[68:71], v[128:131]
	s_waitcnt vmcnt(16)
	ds_write_b128 v105, v[16:19]
	ds_write_b128 v106, v[20:23]
	ds_write_b128 v107, v[24:27]
	ds_write_b128 v108, v[28:31]
	global_load_dwordx4 v[16:19], v72, s[74:75] nt
	global_load_dwordx4 v[20:23], v73, s[74:75] nt
	global_load_dwordx4 v[24:27], v74, s[74:75] nt
	global_load_dwordx4 v[28:31], v75, s[74:75] nt
	s_add_u32 s74, s74, 0x40000
	s_addc_u32 s75, s75, 0
	ds_read_b128 v[216:219], v109
	ds_read_b128 v[220:223], v110
	ds_read_b128 v[224:227], v111
	ds_read_b128 v[228:231], v14
	ds_read_b128 v[132:135], v80 offset:2560
	s_waitcnt lgkmcnt(0)
	v_cvt_pk_bf16_f32 v2, v216, v217
	v_cvt_pk_bf16_f32 v3, v218, v219
	v_cvt_pk_bf16_f32 v4, v220, v221
	v_cvt_pk_bf16_f32 v5, v222, v223
	v_cvt_pk_bf16_f32 v6, v224, v225
	v_cvt_pk_bf16_f32 v7, v226, v227
	v_cvt_pk_bf16_f32 v8, v228, v229
	v_cvt_pk_bf16_f32 v9, v230, v231
	s_nop 0
	v_mfma_f32_16x16x32_bf16 v[132:135], v[2:5], v[64:67], v[132:135]
	v_mfma_f32_16x16x32_bf16 v[132:135], v[6:9], v[68:71], v[132:135]
	s_waitcnt vmcnt(16)
	ds_write_b128 v105, v[32:35]
	ds_write_b128 v106, v[36:39]
	ds_write_b128 v107, v[40:43]
	ds_write_b128 v108, v[44:47]
	global_load_dwordx4 v[32:35], v72, s[74:75] nt
	global_load_dwordx4 v[36:39], v73, s[74:75] nt
	global_load_dwordx4 v[40:43], v74, s[74:75] nt
	global_load_dwordx4 v[44:47], v75, s[74:75] nt
	s_add_u32 s74, s74, 0x40000
	s_addc_u32 s75, s75, 0
	ds_read_b128 v[216:219], v109
	ds_read_b128 v[220:223], v110
	ds_read_b128 v[224:227], v111
	ds_read_b128 v[228:231], v14
	ds_read_b128 v[136:139], v80 offset:3072
	s_waitcnt lgkmcnt(0)
	v_cvt_pk_bf16_f32 v2, v216, v217
	v_cvt_pk_bf16_f32 v3, v218, v219
	v_cvt_pk_bf16_f32 v4, v220, v221
	v_cvt_pk_bf16_f32 v5, v222, v223
	v_cvt_pk_bf16_f32 v6, v224, v225
	v_cvt_pk_bf16_f32 v7, v226, v227
	v_cvt_pk_bf16_f32 v8, v228, v229
	v_cvt_pk_bf16_f32 v9, v230, v231
	s_nop 0
	v_mfma_f32_16x16x32_bf16 v[136:139], v[2:5], v[64:67], v[136:139]
	v_mfma_f32_16x16x32_bf16 v[136:139], v[6:9], v[68:71], v[136:139]
	s_waitcnt vmcnt(16)
	ds_write_b128 v105, v[48:51]
	ds_write_b128 v106, v[52:55]
	ds_write_b128 v107, v[56:59]
	ds_write_b128 v108, v[60:63]
	global_load_dwordx4 v[48:51], v72, s[74:75] nt
	global_load_dwordx4 v[52:55], v73, s[74:75] nt
	global_load_dwordx4 v[56:59], v74, s[74:75] nt
	global_load_dwordx4 v[60:63], v75, s[74:75] nt
	s_add_u32 s74, s74, 0x40000
	s_addc_u32 s75, s75, 0
	ds_read_b128 v[216:219], v109
	ds_read_b128 v[220:223], v110
	ds_read_b128 v[224:227], v111
	ds_read_b128 v[228:231], v14
	ds_read_b128 v[140:143], v80 offset:3584
	s_waitcnt lgkmcnt(0)
	v_cvt_pk_bf16_f32 v2, v216, v217
	v_cvt_pk_bf16_f32 v3, v218, v219
	v_cvt_pk_bf16_f32 v4, v220, v221
	v_cvt_pk_bf16_f32 v5, v222, v223
	v_cvt_pk_bf16_f32 v6, v224, v225
	v_cvt_pk_bf16_f32 v7, v226, v227
	v_cvt_pk_bf16_f32 v8, v228, v229
	v_cvt_pk_bf16_f32 v9, v230, v231
	s_nop 0
	v_mfma_f32_16x16x32_bf16 v[140:143], v[2:5], v[64:67], v[140:143]
	v_mfma_f32_16x16x32_bf16 v[140:143], v[6:9], v[68:71], v[140:143]
	s_waitcnt vmcnt(16)
	ds_write_b128 v105, v[180:183]
	ds_write_b128 v106, v[184:187]
	ds_write_b128 v107, v[188:191]
	ds_write_b128 v108, v[192:195]
	global_load_dwordx4 v[180:183], v72, s[74:75] nt
	global_load_dwordx4 v[184:187], v73, s[74:75] nt
	global_load_dwordx4 v[188:191], v74, s[74:75] nt
	global_load_dwordx4 v[192:195], v75, s[74:75] nt
	s_add_u32 s74, s74, 0x40000
	s_addc_u32 s75, s75, 0
	ds_read_b128 v[216:219], v109
	ds_read_b128 v[220:223], v110
	ds_read_b128 v[224:227], v111
	ds_read_b128 v[228:231], v14
	ds_read_b128 v[144:147], v80 offset:4096
	s_waitcnt lgkmcnt(0)
	v_cvt_pk_bf16_f32 v2, v216, v217
	v_cvt_pk_bf16_f32 v3, v218, v219
	v_cvt_pk_bf16_f32 v4, v220, v221
	v_cvt_pk_bf16_f32 v5, v222, v223
	v_cvt_pk_bf16_f32 v6, v224, v225
	v_cvt_pk_bf16_f32 v7, v226, v227
	v_cvt_pk_bf16_f32 v8, v228, v229
	v_cvt_pk_bf16_f32 v9, v230, v231
	s_nop 0
	v_mfma_f32_16x16x32_bf16 v[144:147], v[2:5], v[64:67], v[144:147]
	v_mfma_f32_16x16x32_bf16 v[144:147], v[6:9], v[68:71], v[144:147]
	s_waitcnt vmcnt(16)
	ds_write_b128 v105, v[200:203]
	ds_write_b128 v106, v[204:207]
	ds_write_b128 v107, v[208:211]
	ds_write_b128 v108, v[212:215]
	global_load_dwordx4 v[200:203], v72, s[74:75] nt
	global_load_dwordx4 v[204:207], v73, s[74:75] nt
	global_load_dwordx4 v[208:211], v74, s[74:75] nt
	global_load_dwordx4 v[212:215], v75, s[74:75] nt
	s_add_u32 s74, s74, 0x40000
	s_addc_u32 s75, s75, 0
	ds_read_b128 v[216:219], v109
	ds_read_b128 v[220:223], v110
	ds_read_b128 v[224:227], v111
	ds_read_b128 v[228:231], v14
	ds_read_b128 v[148:151], v80 offset:4608
	s_waitcnt lgkmcnt(0)
	v_cvt_pk_bf16_f32 v2, v216, v217
	v_cvt_pk_bf16_f32 v3, v218, v219
	v_cvt_pk_bf16_f32 v4, v220, v221
	v_cvt_pk_bf16_f32 v5, v222, v223
	v_cvt_pk_bf16_f32 v6, v224, v225
	v_cvt_pk_bf16_f32 v7, v226, v227
	v_cvt_pk_bf16_f32 v8, v228, v229
	v_cvt_pk_bf16_f32 v9, v230, v231
	s_nop 0
	v_mfma_f32_16x16x32_bf16 v[148:151], v[2:5], v[64:67], v[148:151]
	v_mfma_f32_16x16x32_bf16 v[148:151], v[6:9], v[68:71], v[148:151]
	s_waitcnt vmcnt(16)
	ds_write_b128 v105, v[16:19]
	ds_write_b128 v106, v[20:23]
	ds_write_b128 v107, v[24:27]
	ds_write_b128 v108, v[28:31]
	global_load_dwordx4 v[16:19], v72, s[74:75] nt
	global_load_dwordx4 v[20:23], v73, s[74:75] nt
	global_load_dwordx4 v[24:27], v74, s[74:75] nt
	global_load_dwordx4 v[28:31], v75, s[74:75] nt
	s_add_u32 s74, s74, 0x40000
	s_addc_u32 s75, s75, 0
	ds_read_b128 v[216:219], v109
	ds_read_b128 v[220:223], v110
	ds_read_b128 v[224:227], v111
	ds_read_b128 v[228:231], v14
	ds_read_b128 v[152:155], v80 offset:5120
	s_waitcnt lgkmcnt(0)
	v_cvt_pk_bf16_f32 v2, v216, v217
	v_cvt_pk_bf16_f32 v3, v218, v219
	v_cvt_pk_bf16_f32 v4, v220, v221
	v_cvt_pk_bf16_f32 v5, v222, v223
	v_cvt_pk_bf16_f32 v6, v224, v225
	v_cvt_pk_bf16_f32 v7, v226, v227
	v_cvt_pk_bf16_f32 v8, v228, v229
	v_cvt_pk_bf16_f32 v9, v230, v231
	s_nop 0
	v_mfma_f32_16x16x32_bf16 v[152:155], v[2:5], v[64:67], v[152:155]
	v_mfma_f32_16x16x32_bf16 v[152:155], v[6:9], v[68:71], v[152:155]
	s_waitcnt vmcnt(16)
	ds_write_b128 v105, v[32:35]
	ds_write_b128 v106, v[36:39]
	ds_write_b128 v107, v[40:43]
	ds_write_b128 v108, v[44:47]
	ds_read_b128 v[216:219], v109
	ds_read_b128 v[220:223], v110
	ds_read_b128 v[224:227], v111
	ds_read_b128 v[228:231], v14
	ds_read_b128 v[156:159], v80 offset:5632
	s_waitcnt lgkmcnt(0)
	v_cvt_pk_bf16_f32 v2, v216, v217
	v_cvt_pk_bf16_f32 v3, v218, v219
	v_cvt_pk_bf16_f32 v4, v220, v221
	v_cvt_pk_bf16_f32 v5, v222, v223
	v_cvt_pk_bf16_f32 v6, v224, v225
	v_cvt_pk_bf16_f32 v7, v226, v227
	v_cvt_pk_bf16_f32 v8, v228, v229
	v_cvt_pk_bf16_f32 v9, v230, v231
	s_nop 0
	v_mfma_f32_16x16x32_bf16 v[156:159], v[2:5], v[64:67], v[156:159]
	v_mfma_f32_16x16x32_bf16 v[156:159], v[6:9], v[68:71], v[156:159]
	s_waitcnt vmcnt(12)
	ds_write_b128 v105, v[48:51]
	ds_write_b128 v106, v[52:55]
	ds_write_b128 v107, v[56:59]
	ds_write_b128 v108, v[60:63]
	ds_read_b128 v[216:219], v109
	ds_read_b128 v[220:223], v110
	ds_read_b128 v[224:227], v111
	ds_read_b128 v[228:231], v14
	ds_read_b128 v[160:163], v80 offset:6144
	s_waitcnt lgkmcnt(0)
	v_cvt_pk_bf16_f32 v2, v216, v217
	v_cvt_pk_bf16_f32 v3, v218, v219
	v_cvt_pk_bf16_f32 v4, v220, v221
	v_cvt_pk_bf16_f32 v5, v222, v223
	v_cvt_pk_bf16_f32 v6, v224, v225
	v_cvt_pk_bf16_f32 v7, v226, v227
	v_cvt_pk_bf16_f32 v8, v228, v229
	v_cvt_pk_bf16_f32 v9, v230, v231
	s_nop 0
	v_mfma_f32_16x16x32_bf16 v[160:163], v[2:5], v[64:67], v[160:163]
	v_mfma_f32_16x16x32_bf16 v[160:163], v[6:9], v[68:71], v[160:163]
	s_waitcnt vmcnt(8)
	ds_write_b128 v105, v[180:183]
	ds_write_b128 v106, v[184:187]
	ds_write_b128 v107, v[188:191]
	ds_write_b128 v108, v[192:195]
	ds_read_b128 v[216:219], v109
	ds_read_b128 v[220:223], v110
	ds_read_b128 v[224:227], v111
	ds_read_b128 v[228:231], v14
	ds_read_b128 v[164:167], v80 offset:6656
	s_waitcnt lgkmcnt(0)
	v_cvt_pk_bf16_f32 v2, v216, v217
	v_cvt_pk_bf16_f32 v3, v218, v219
	v_cvt_pk_bf16_f32 v4, v220, v221
	v_cvt_pk_bf16_f32 v5, v222, v223
	v_cvt_pk_bf16_f32 v6, v224, v225
	v_cvt_pk_bf16_f32 v7, v226, v227
	v_cvt_pk_bf16_f32 v8, v228, v229
	v_cvt_pk_bf16_f32 v9, v230, v231
	s_nop 0
	v_mfma_f32_16x16x32_bf16 v[164:167], v[2:5], v[64:67], v[164:167]
	v_mfma_f32_16x16x32_bf16 v[164:167], v[6:9], v[68:71], v[164:167]
	s_waitcnt vmcnt(4)
	ds_write_b128 v105, v[200:203]
	ds_write_b128 v106, v[204:207]
	ds_write_b128 v107, v[208:211]
	ds_write_b128 v108, v[212:215]
	ds_read_b128 v[216:219], v109
	ds_read_b128 v[220:223], v110
	ds_read_b128 v[224:227], v111
	ds_read_b128 v[228:231], v14
	ds_read_b128 v[168:171], v80 offset:7168
	s_waitcnt lgkmcnt(0)
	v_cvt_pk_bf16_f32 v2, v216, v217
	v_cvt_pk_bf16_f32 v3, v218, v219
	v_cvt_pk_bf16_f32 v4, v220, v221
	v_cvt_pk_bf16_f32 v5, v222, v223
	v_cvt_pk_bf16_f32 v6, v224, v225
	v_cvt_pk_bf16_f32 v7, v226, v227
	v_cvt_pk_bf16_f32 v8, v228, v229
	v_cvt_pk_bf16_f32 v9, v230, v231
	s_nop 0
	v_mfma_f32_16x16x32_bf16 v[168:171], v[2:5], v[64:67], v[168:171]
	v_mfma_f32_16x16x32_bf16 v[168:171], v[6:9], v[68:71], v[168:171]
	s_waitcnt vmcnt(0)
	ds_write_b128 v105, v[16:19]
	ds_write_b128 v106, v[20:23]
	ds_write_b128 v107, v[24:27]
	ds_write_b128 v108, v[28:31]
	ds_read_b128 v[216:219], v109
	ds_read_b128 v[220:223], v110
	ds_read_b128 v[224:227], v111
	ds_read_b128 v[228:231], v14
	ds_read_b128 v[172:175], v80 offset:7680
	s_waitcnt lgkmcnt(0)
	v_cvt_pk_bf16_f32 v2, v216, v217
	v_cvt_pk_bf16_f32 v3, v218, v219
	v_cvt_pk_bf16_f32 v4, v220, v221
	v_cvt_pk_bf16_f32 v5, v222, v223
	v_cvt_pk_bf16_f32 v6, v224, v225
	v_cvt_pk_bf16_f32 v7, v226, v227
	v_cvt_pk_bf16_f32 v8, v228, v229
	v_cvt_pk_bf16_f32 v9, v230, v231
	s_nop 0
	v_mfma_f32_16x16x32_bf16 v[172:175], v[2:5], v[64:67], v[172:175]
	v_mfma_f32_16x16x32_bf16 v[172:175], v[6:9], v[68:71], v[172:175]
	s_cmp_lg_u32 s72, 0
	s_cbranch_scc1 .Lsa_t16_skip
	v_mov_b32_e32 v15, 0x2010
	v_lshl_add_u32 v15, v76, 4, v15
	ds_write_b128 v105, v[232:235]
	ds_write_b128 v106, v[236:239]
	ds_write_b128 v107, v[240:243]
	ds_write_b128 v108, v[244:247]
	global_load_dwordx4 v[232:235], v72, s[84:85] nt
	global_load_dwordx4 v[236:239], v73, s[84:85] nt
	global_load_dwordx4 v[240:243], v74, s[84:85] nt
	global_load_dwordx4 v[244:247], v75, s[84:85] nt
	ds_read_b128 v[216:219], v109
	ds_read_b128 v[220:223], v110
	ds_read_b128 v[224:227], v111
	ds_read_b128 v[228:231], v14
	ds_read_b128 v[176:179], v15
	s_waitcnt lgkmcnt(0)
	v_cvt_pk_bf16_f32 v2, v216, v217
	v_cvt_pk_bf16_f32 v3, v218, v219
	v_cvt_pk_bf16_f32 v4, v220, v221
	v_cvt_pk_bf16_f32 v5, v222, v223
	v_cvt_pk_bf16_f32 v6, v224, v225
	v_cvt_pk_bf16_f32 v7, v226, v227
	v_cvt_pk_bf16_f32 v8, v228, v229
	v_cvt_pk_bf16_f32 v9, v230, v231
	s_nop 0
	v_mfma_f32_16x16x32_bf16 v[176:179], v[2:5], v[64:67], v[176:179]
	v_mfma_f32_16x16x32_bf16 v[176:179], v[6:9], v[68:71], v[176:179]
	v_lshlrev_b32_e32 v15, 2, v76
	s_nop 7
	s_nop 1
	v_add_u32_e32 v78, 0, v15
	v_cmp_gt_u32_e32 vcc, v78, v77
	s_nop 1
	v_cndmask_b32_e32 v176, v176, v101, vcc
	v_add_u32_e32 v78, 1, v15
	v_cmp_gt_u32_e32 vcc, v78, v77
	s_nop 1
	v_cndmask_b32_e32 v177, v177, v101, vcc
	v_add_u32_e32 v78, 2, v15
	v_cmp_gt_u32_e32 vcc, v78, v77
	s_nop 1
	v_cndmask_b32_e32 v178, v178, v101, vcc
	v_add_u32_e32 v78, 3, v15
	v_cmp_gt_u32_e32 vcc, v78, v77
	s_nop 1
	v_cndmask_b32_e32 v179, v179, v101, vcc
.Lsa_t16_skip:
	global_load_dwordx4 v[16:19], v72, s[76:77] nt
	global_load_dwordx4 v[20:23], v73, s[76:77] nt
	global_load_dwordx4 v[24:27], v74, s[76:77] nt
	global_load_dwordx4 v[28:31], v75, s[76:77] nt
	global_load_dwordx4 v[32:35], v72, s[78:79] nt
	global_load_dwordx4 v[36:39], v73, s[78:79] nt
	global_load_dwordx4 v[40:43], v74, s[78:79] nt
	global_load_dwordx4 v[44:47], v75, s[78:79] nt
	s_add_u32 s76, s76, 0x80000
	s_addc_u32 s77, s77, 0
	s_add_u32 s78, s78, 0x80000
	s_addc_u32 s79, s79, 0
	global_load_dwordx4 v[48:51], v72, s[76:77] nt
	global_load_dwordx4 v[52:55], v73, s[76:77] nt
	global_load_dwordx4 v[56:59], v74, s[76:77] nt
	global_load_dwordx4 v[60:63], v75, s[76:77] nt
	global_load_dwordx4 v[200:203], v72, s[78:79] nt
	global_load_dwordx4 v[204:207], v73, s[78:79] nt
	global_load_dwordx4 v[208:211], v74, s[78:79] nt
	global_load_dwordx4 v[212:215], v75, s[78:79] nt
	s_add_u32 s76, s76, 0x80000
	s_addc_u32 s77, s77, 0
	s_add_u32 s78, s78, 0x80000
	s_addc_u32 s79, s79, 0
	s_nop 7
	s_nop 1
	v_max3_f32 v248, v112, v113, v114
	v_max3_f32 v248, v248, v115, v116
	v_max3_f32 v248, v248, v117, v118
	v_max3_f32 v248, v248, v119, v120
	v_max3_f32 v248, v248, v121, v122
	v_max3_f32 v248, v248, v123, v124
	v_max3_f32 v248, v248, v125, v126
	v_max3_f32 v248, v248, v127, v128
	v_max3_f32 v248, v248, v129, v130
	v_max3_f32 v248, v248, v131, v132
	v_max3_f32 v248, v248, v133, v134
	v_max3_f32 v248, v248, v135, v136
	v_max3_f32 v248, v248, v137, v138
	v_max3_f32 v248, v248, v139, v140
	v_max3_f32 v248, v248, v141, v142
	v_max3_f32 v248, v248, v143, v144
	v_max3_f32 v248, v248, v145, v146
	v_max3_f32 v248, v248, v147, v148
	v_max3_f32 v248, v248, v149, v150
	v_max3_f32 v248, v248, v151, v152
	v_max3_f32 v248, v248, v153, v154
	v_max3_f32 v248, v248, v155, v156
	v_max3_f32 v248, v248, v157, v158
	v_max3_f32 v248, v248, v159, v160
	v_max3_f32 v248, v248, v161, v162
	v_max3_f32 v248, v248, v163, v164
	v_max3_f32 v248, v248, v165, v166
	v_max3_f32 v248, v248, v167, v168
	v_max3_f32 v248, v248, v169, v170
	v_max3_f32 v248, v248, v171, v172
	v_max3_f32 v248, v248, v173, v174
	v_max3_f32 v248, v248, v175, v176
	v_max3_f32 v248, v248, v177, v178
	v_max3_f32 v248, v248, v179, v179
	ds_write_b32 v81, v248 offset:49168
	v_lshlrev_b32_e32 v105, 2, v77
	v_add_u32_e32 v105, 0xc010, v105
	v_add_u32_e32 v106, 64, v105
	v_add_u32_e32 v107, 0x80, v105
	v_add_u32_e32 v108, 0xc0, v105
	s_waitcnt lgkmcnt(0)
	s_barrier
	ds_read2st64_b32 v[180:181], v105 offset0:0 offset1:1
	ds_read2st64_b32 v[182:183], v105 offset0:2 offset1:3
	ds_read2st64_b32 v[184:185], v105 offset0:4 offset1:5
	ds_read2st64_b32 v[186:187], v105 offset0:6 offset1:7
	ds_read2st64_b32 v[188:189], v106 offset0:0 offset1:1
	ds_read2st64_b32 v[190:191], v106 offset0:2 offset1:3
	ds_read2st64_b32 v[192:193], v106 offset0:4 offset1:5
	ds_read2st64_b32 v[194:195], v106 offset0:6 offset1:7
	ds_read2st64_b32 v[216:217], v107 offset0:0 offset1:1
	ds_read2st64_b32 v[218:219], v107 offset0:2 offset1:3
	ds_read2st64_b32 v[220:221], v107 offset0:4 offset1:5
	ds_read2st64_b32 v[222:223], v107 offset0:6 offset1:7
	ds_read2st64_b32 v[224:225], v108 offset0:0 offset1:1
	ds_read2st64_b32 v[226:227], v108 offset0:2 offset1:3
	ds_read2st64_b32 v[228:229], v108 offset0:4 offset1:5
	ds_read2st64_b32 v[230:231], v108 offset0:6 offset1:7
	s_waitcnt lgkmcnt(0)
	v_max3_f32 v248, v180, v181, v182
	v_max3_f32 v248, v248, v183, v184
	v_max3_f32 v248, v248, v185, v186
	v_max3_f32 v248, v248, v187, v188
	v_max3_f32 v248, v248, v189, v190
	v_max3_f32 v248, v248, v191, v192
	v_max3_f32 v248, v248, v193, v194
	v_max3_f32 v248, v248, v195, v216
	v_max3_f32 v248, v248, v217, v218
	v_max3_f32 v248, v248, v219, v220
	v_max3_f32 v248, v248, v221, v222
	v_max3_f32 v248, v248, v223, v224
	v_max3_f32 v248, v248, v225, v226
	v_max3_f32 v248, v248, v227, v228
	v_max3_f32 v248, v248, v229, v230
	v_max3_f32 v248, v248, v231, v231
	v_mov_b32_e32 v249, 0
	v_sub_f32_e32 v112, v112, v248
	v_sub_f32_e32 v113, v113, v248
	v_sub_f32_e32 v114, v114, v248
	v_sub_f32_e32 v115, v115, v248
	v_cmp_gt_f32_e64 s[24:25], s61, v112
	v_cmp_gt_f32_e64 s[26:27], s61, v113
	v_cmp_gt_f32_e64 s[28:29], s61, v114
	v_cmp_gt_f32_e64 s[34:35], s61, v115
	v_cndmask_b32_e64 v180, 0, v102, s[24:25]
	v_cndmask_b32_e64 v181, 0, v102, s[26:27]
	v_cndmask_b32_e64 v182, 0, v102, s[28:29]
	v_cndmask_b32_e64 v183, 0, v102, s[34:35]
	v_add_f32_e32 v112, v112, v180
	v_add_f32_e32 v113, v113, v181
	v_add_f32_e32 v114, v114, v182
	v_add_f32_e32 v115, v115, v183
	v_exp_f32_e32 v112, v112
	v_exp_f32_e32 v113, v113
	v_exp_f32_e32 v114, v114
	v_exp_f32_e32 v115, v115
	v_cndmask_b32_e64 v180, 0, v103, s[24:25]
	v_cndmask_b32_e64 v181, 0, v103, s[26:27]
	v_cndmask_b32_e64 v182, 0, v103, s[28:29]
	v_cndmask_b32_e64 v183, 0, v103, s[34:35]
	v_ldexp_f32 v112, v112, v180
	v_ldexp_f32 v113, v113, v181
	v_ldexp_f32 v114, v114, v182
	v_ldexp_f32 v115, v115, v183
	v_add_f32_e32 v249, v249, v112
	v_add_f32_e32 v249, v249, v113
	v_add_f32_e32 v249, v249, v114
	v_add_f32_e32 v249, v249, v115
	v_sub_f32_e32 v116, v116, v248
	v_sub_f32_e32 v117, v117, v248
	v_sub_f32_e32 v118, v118, v248
	v_sub_f32_e32 v119, v119, v248
	v_cmp_gt_f32_e64 s[24:25], s61, v116
	v_cmp_gt_f32_e64 s[26:27], s61, v117
	v_cmp_gt_f32_e64 s[28:29], s61, v118
	v_cmp_gt_f32_e64 s[34:35], s61, v119
	v_cndmask_b32_e64 v180, 0, v102, s[24:25]
	v_cndmask_b32_e64 v181, 0, v102, s[26:27]
	v_cndmask_b32_e64 v182, 0, v102, s[28:29]
	v_cndmask_b32_e64 v183, 0, v102, s[34:35]
	v_add_f32_e32 v116, v116, v180
	v_add_f32_e32 v117, v117, v181
	v_add_f32_e32 v118, v118, v182
	v_add_f32_e32 v119, v119, v183
	v_exp_f32_e32 v116, v116
	v_exp_f32_e32 v117, v117
	v_exp_f32_e32 v118, v118
	v_exp_f32_e32 v119, v119
	v_cndmask_b32_e64 v180, 0, v103, s[24:25]
	v_cndmask_b32_e64 v181, 0, v103, s[26:27]
	v_cndmask_b32_e64 v182, 0, v103, s[28:29]
	v_cndmask_b32_e64 v183, 0, v103, s[34:35]
	v_ldexp_f32 v116, v116, v180
	v_ldexp_f32 v117, v117, v181
	v_ldexp_f32 v118, v118, v182
	v_ldexp_f32 v119, v119, v183
	v_add_f32_e32 v249, v249, v116
	v_add_f32_e32 v249, v249, v117
	v_add_f32_e32 v249, v249, v118
	v_add_f32_e32 v249, v249, v119
	v_sub_f32_e32 v120, v120, v248
	v_sub_f32_e32 v121, v121, v248
	v_sub_f32_e32 v122, v122, v248
	v_sub_f32_e32 v123, v123, v248
	v_cmp_gt_f32_e64 s[24:25], s61, v120
	v_cmp_gt_f32_e64 s[26:27], s61, v121
	v_cmp_gt_f32_e64 s[28:29], s61, v122
	v_cmp_gt_f32_e64 s[34:35], s61, v123
	v_cndmask_b32_e64 v180, 0, v102, s[24:25]
	v_cndmask_b32_e64 v181, 0, v102, s[26:27]
	v_cndmask_b32_e64 v182, 0, v102, s[28:29]
	v_cndmask_b32_e64 v183, 0, v102, s[34:35]
	v_add_f32_e32 v120, v120, v180
	v_add_f32_e32 v121, v121, v181
	v_add_f32_e32 v122, v122, v182
	v_add_f32_e32 v123, v123, v183
	v_exp_f32_e32 v120, v120
	v_exp_f32_e32 v121, v121
	v_exp_f32_e32 v122, v122
	v_exp_f32_e32 v123, v123
	v_cndmask_b32_e64 v180, 0, v103, s[24:25]
	v_cndmask_b32_e64 v181, 0, v103, s[26:27]
	v_cndmask_b32_e64 v182, 0, v103, s[28:29]
	v_cndmask_b32_e64 v183, 0, v103, s[34:35]
	v_ldexp_f32 v120, v120, v180
	v_ldexp_f32 v121, v121, v181
	v_ldexp_f32 v122, v122, v182
	v_ldexp_f32 v123, v123, v183
	v_add_f32_e32 v249, v249, v120
	v_add_f32_e32 v249, v249, v121
	v_add_f32_e32 v249, v249, v122
	v_add_f32_e32 v249, v249, v123
	v_sub_f32_e32 v124, v124, v248
	v_sub_f32_e32 v125, v125, v248
	v_sub_f32_e32 v126, v126, v248
	v_sub_f32_e32 v127, v127, v248
	v_cmp_gt_f32_e64 s[24:25], s61, v124
	v_cmp_gt_f32_e64 s[26:27], s61, v125
	v_cmp_gt_f32_e64 s[28:29], s61, v126
	v_cmp_gt_f32_e64 s[34:35], s61, v127
	v_cndmask_b32_e64 v180, 0, v102, s[24:25]
	v_cndmask_b32_e64 v181, 0, v102, s[26:27]
	v_cndmask_b32_e64 v182, 0, v102, s[28:29]
	v_cndmask_b32_e64 v183, 0, v102, s[34:35]
	v_add_f32_e32 v124, v124, v180
	v_add_f32_e32 v125, v125, v181
	v_add_f32_e32 v126, v126, v182
	v_add_f32_e32 v127, v127, v183
	v_exp_f32_e32 v124, v124
	v_exp_f32_e32 v125, v125
	v_exp_f32_e32 v126, v126
	v_exp_f32_e32 v127, v127
	v_cndmask_b32_e64 v180, 0, v103, s[24:25]
	v_cndmask_b32_e64 v181, 0, v103, s[26:27]
	v_cndmask_b32_e64 v182, 0, v103, s[28:29]
	v_cndmask_b32_e64 v183, 0, v103, s[34:35]
	v_ldexp_f32 v124, v124, v180
	v_ldexp_f32 v125, v125, v181
	v_ldexp_f32 v126, v126, v182
	v_ldexp_f32 v127, v127, v183
	v_add_f32_e32 v249, v249, v124
	v_add_f32_e32 v249, v249, v125
	v_add_f32_e32 v249, v249, v126
	v_add_f32_e32 v249, v249, v127
	v_sub_f32_e32 v128, v128, v248
	v_sub_f32_e32 v129, v129, v248
	v_sub_f32_e32 v130, v130, v248
	v_sub_f32_e32 v131, v131, v248
	v_cmp_gt_f32_e64 s[24:25], s61, v128
	v_cmp_gt_f32_e64 s[26:27], s61, v129
	v_cmp_gt_f32_e64 s[28:29], s61, v130
	v_cmp_gt_f32_e64 s[34:35], s61, v131
	v_cndmask_b32_e64 v180, 0, v102, s[24:25]
	v_cndmask_b32_e64 v181, 0, v102, s[26:27]
	v_cndmask_b32_e64 v182, 0, v102, s[28:29]
	v_cndmask_b32_e64 v183, 0, v102, s[34:35]
	v_add_f32_e32 v128, v128, v180
	v_add_f32_e32 v129, v129, v181
	v_add_f32_e32 v130, v130, v182
	v_add_f32_e32 v131, v131, v183
	v_exp_f32_e32 v128, v128
	v_exp_f32_e32 v129, v129
	v_exp_f32_e32 v130, v130
	v_exp_f32_e32 v131, v131
	v_cndmask_b32_e64 v180, 0, v103, s[24:25]
	v_cndmask_b32_e64 v181, 0, v103, s[26:27]
	v_cndmask_b32_e64 v182, 0, v103, s[28:29]
	v_cndmask_b32_e64 v183, 0, v103, s[34:35]
	v_ldexp_f32 v128, v128, v180
	v_ldexp_f32 v129, v129, v181
	v_ldexp_f32 v130, v130, v182
	v_ldexp_f32 v131, v131, v183
	v_add_f32_e32 v249, v249, v128
	v_add_f32_e32 v249, v249, v129
	v_add_f32_e32 v249, v249, v130
	v_add_f32_e32 v249, v249, v131
	v_sub_f32_e32 v132, v132, v248
	v_sub_f32_e32 v133, v133, v248
	v_sub_f32_e32 v134, v134, v248
	v_sub_f32_e32 v135, v135, v248
	v_cmp_gt_f32_e64 s[24:25], s61, v132
	v_cmp_gt_f32_e64 s[26:27], s61, v133
	v_cmp_gt_f32_e64 s[28:29], s61, v134
	v_cmp_gt_f32_e64 s[34:35], s61, v135
	v_cndmask_b32_e64 v180, 0, v102, s[24:25]
	v_cndmask_b32_e64 v181, 0, v102, s[26:27]
	v_cndmask_b32_e64 v182, 0, v102, s[28:29]
	v_cndmask_b32_e64 v183, 0, v102, s[34:35]
	v_add_f32_e32 v132, v132, v180
	v_add_f32_e32 v133, v133, v181
	v_add_f32_e32 v134, v134, v182
	v_add_f32_e32 v135, v135, v183
	v_exp_f32_e32 v132, v132
	v_exp_f32_e32 v133, v133
	v_exp_f32_e32 v134, v134
	v_exp_f32_e32 v135, v135
	v_cndmask_b32_e64 v180, 0, v103, s[24:25]
	v_cndmask_b32_e64 v181, 0, v103, s[26:27]
	v_cndmask_b32_e64 v182, 0, v103, s[28:29]
	v_cndmask_b32_e64 v183, 0, v103, s[34:35]
	v_ldexp_f32 v132, v132, v180
	v_ldexp_f32 v133, v133, v181
	v_ldexp_f32 v134, v134, v182
	v_ldexp_f32 v135, v135, v183
	v_add_f32_e32 v249, v249, v132
	v_add_f32_e32 v249, v249, v133
	v_add_f32_e32 v249, v249, v134
	v_add_f32_e32 v249, v249, v135
	v_sub_f32_e32 v136, v136, v248
	v_sub_f32_e32 v137, v137, v248
	v_sub_f32_e32 v138, v138, v248
	v_sub_f32_e32 v139, v139, v248
	v_cmp_gt_f32_e64 s[24:25], s61, v136
	v_cmp_gt_f32_e64 s[26:27], s61, v137
	v_cmp_gt_f32_e64 s[28:29], s61, v138
	v_cmp_gt_f32_e64 s[34:35], s61, v139
	v_cndmask_b32_e64 v180, 0, v102, s[24:25]
	v_cndmask_b32_e64 v181, 0, v102, s[26:27]
	v_cndmask_b32_e64 v182, 0, v102, s[28:29]
	v_cndmask_b32_e64 v183, 0, v102, s[34:35]
	v_add_f32_e32 v136, v136, v180
	v_add_f32_e32 v137, v137, v181
	v_add_f32_e32 v138, v138, v182
	v_add_f32_e32 v139, v139, v183
	v_exp_f32_e32 v136, v136
	v_exp_f32_e32 v137, v137
	v_exp_f32_e32 v138, v138
	v_exp_f32_e32 v139, v139
	v_cndmask_b32_e64 v180, 0, v103, s[24:25]
	v_cndmask_b32_e64 v181, 0, v103, s[26:27]
	v_cndmask_b32_e64 v182, 0, v103, s[28:29]
	v_cndmask_b32_e64 v183, 0, v103, s[34:35]
	v_ldexp_f32 v136, v136, v180
	v_ldexp_f32 v137, v137, v181
	v_ldexp_f32 v138, v138, v182
	v_ldexp_f32 v139, v139, v183
	v_add_f32_e32 v249, v249, v136
	v_add_f32_e32 v249, v249, v137
	v_add_f32_e32 v249, v249, v138
	v_add_f32_e32 v249, v249, v139
	v_sub_f32_e32 v140, v140, v248
	v_sub_f32_e32 v141, v141, v248
	v_sub_f32_e32 v142, v142, v248
	v_sub_f32_e32 v143, v143, v248
	v_cmp_gt_f32_e64 s[24:25], s61, v140
	v_cmp_gt_f32_e64 s[26:27], s61, v141
	v_cmp_gt_f32_e64 s[28:29], s61, v142
	v_cmp_gt_f32_e64 s[34:35], s61, v143
	v_cndmask_b32_e64 v180, 0, v102, s[24:25]
	v_cndmask_b32_e64 v181, 0, v102, s[26:27]
	v_cndmask_b32_e64 v182, 0, v102, s[28:29]
	v_cndmask_b32_e64 v183, 0, v102, s[34:35]
	v_add_f32_e32 v140, v140, v180
	v_add_f32_e32 v141, v141, v181
	v_add_f32_e32 v142, v142, v182
	v_add_f32_e32 v143, v143, v183
	v_exp_f32_e32 v140, v140
	v_exp_f32_e32 v141, v141
	v_exp_f32_e32 v142, v142
	v_exp_f32_e32 v143, v143
	v_cndmask_b32_e64 v180, 0, v103, s[24:25]
	v_cndmask_b32_e64 v181, 0, v103, s[26:27]
	v_cndmask_b32_e64 v182, 0, v103, s[28:29]
	v_cndmask_b32_e64 v183, 0, v103, s[34:35]
	v_ldexp_f32 v140, v140, v180
	v_ldexp_f32 v141, v141, v181
	v_ldexp_f32 v142, v142, v182
	v_ldexp_f32 v143, v143, v183
	v_add_f32_e32 v249, v249, v140
	v_add_f32_e32 v249, v249, v141
	v_add_f32_e32 v249, v249, v142
	v_add_f32_e32 v249, v249, v143
	v_sub_f32_e32 v144, v144, v248
	v_sub_f32_e32 v145, v145, v248
	v_sub_f32_e32 v146, v146, v248
	v_sub_f32_e32 v147, v147, v248
	v_cmp_gt_f32_e64 s[24:25], s61, v144
	v_cmp_gt_f32_e64 s[26:27], s61, v145
	v_cmp_gt_f32_e64 s[28:29], s61, v146
	v_cmp_gt_f32_e64 s[34:35], s61, v147
	v_cndmask_b32_e64 v180, 0, v102, s[24:25]
	v_cndmask_b32_e64 v181, 0, v102, s[26:27]
	v_cndmask_b32_e64 v182, 0, v102, s[28:29]
	v_cndmask_b32_e64 v183, 0, v102, s[34:35]
	v_add_f32_e32 v144, v144, v180
	v_add_f32_e32 v145, v145, v181
	v_add_f32_e32 v146, v146, v182
	v_add_f32_e32 v147, v147, v183
	v_exp_f32_e32 v144, v144
	v_exp_f32_e32 v145, v145
	v_exp_f32_e32 v146, v146
	v_exp_f32_e32 v147, v147
	v_cndmask_b32_e64 v180, 0, v103, s[24:25]
	v_cndmask_b32_e64 v181, 0, v103, s[26:27]
	v_cndmask_b32_e64 v182, 0, v103, s[28:29]
	v_cndmask_b32_e64 v183, 0, v103, s[34:35]
	v_ldexp_f32 v144, v144, v180
	v_ldexp_f32 v145, v145, v181
	v_ldexp_f32 v146, v146, v182
	v_ldexp_f32 v147, v147, v183
	v_add_f32_e32 v249, v249, v144
	v_add_f32_e32 v249, v249, v145
	v_add_f32_e32 v249, v249, v146
	v_add_f32_e32 v249, v249, v147
	v_sub_f32_e32 v148, v148, v248
	v_sub_f32_e32 v149, v149, v248
	v_sub_f32_e32 v150, v150, v248
	v_sub_f32_e32 v151, v151, v248
	v_cmp_gt_f32_e64 s[24:25], s61, v148
	v_cmp_gt_f32_e64 s[26:27], s61, v149
	v_cmp_gt_f32_e64 s[28:29], s61, v150
	v_cmp_gt_f32_e64 s[34:35], s61, v151
	v_cndmask_b32_e64 v180, 0, v102, s[24:25]
	v_cndmask_b32_e64 v181, 0, v102, s[26:27]
	v_cndmask_b32_e64 v182, 0, v102, s[28:29]
	v_cndmask_b32_e64 v183, 0, v102, s[34:35]
	v_add_f32_e32 v148, v148, v180
	v_add_f32_e32 v149, v149, v181
	v_add_f32_e32 v150, v150, v182
	v_add_f32_e32 v151, v151, v183
	v_exp_f32_e32 v148, v148
	v_exp_f32_e32 v149, v149
	v_exp_f32_e32 v150, v150
	v_exp_f32_e32 v151, v151
	v_cndmask_b32_e64 v180, 0, v103, s[24:25]
	v_cndmask_b32_e64 v181, 0, v103, s[26:27]
	v_cndmask_b32_e64 v182, 0, v103, s[28:29]
	v_cndmask_b32_e64 v183, 0, v103, s[34:35]
	v_ldexp_f32 v148, v148, v180
	v_ldexp_f32 v149, v149, v181
	v_ldexp_f32 v150, v150, v182
	v_ldexp_f32 v151, v151, v183
	v_add_f32_e32 v249, v249, v148
	v_add_f32_e32 v249, v249, v149
	v_add_f32_e32 v249, v249, v150
	v_add_f32_e32 v249, v249, v151
	v_sub_f32_e32 v152, v152, v248
	v_sub_f32_e32 v153, v153, v248
	v_sub_f32_e32 v154, v154, v248
	v_sub_f32_e32 v155, v155, v248
	v_cmp_gt_f32_e64 s[24:25], s61, v152
	v_cmp_gt_f32_e64 s[26:27], s61, v153
	v_cmp_gt_f32_e64 s[28:29], s61, v154
	v_cmp_gt_f32_e64 s[34:35], s61, v155
	v_cndmask_b32_e64 v180, 0, v102, s[24:25]
	v_cndmask_b32_e64 v181, 0, v102, s[26:27]
	v_cndmask_b32_e64 v182, 0, v102, s[28:29]
	v_cndmask_b32_e64 v183, 0, v102, s[34:35]
	v_add_f32_e32 v152, v152, v180
	v_add_f32_e32 v153, v153, v181
	v_add_f32_e32 v154, v154, v182
	v_add_f32_e32 v155, v155, v183
	v_exp_f32_e32 v152, v152
	v_exp_f32_e32 v153, v153
	v_exp_f32_e32 v154, v154
	v_exp_f32_e32 v155, v155
	v_cndmask_b32_e64 v180, 0, v103, s[24:25]
	v_cndmask_b32_e64 v181, 0, v103, s[26:27]
	v_cndmask_b32_e64 v182, 0, v103, s[28:29]
	v_cndmask_b32_e64 v183, 0, v103, s[34:35]
	v_ldexp_f32 v152, v152, v180
	v_ldexp_f32 v153, v153, v181
	v_ldexp_f32 v154, v154, v182
	v_ldexp_f32 v155, v155, v183
	v_add_f32_e32 v249, v249, v152
	v_add_f32_e32 v249, v249, v153
	v_add_f32_e32 v249, v249, v154
	v_add_f32_e32 v249, v249, v155
	v_sub_f32_e32 v156, v156, v248
	v_sub_f32_e32 v157, v157, v248
	v_sub_f32_e32 v158, v158, v248
	v_sub_f32_e32 v159, v159, v248
	v_cmp_gt_f32_e64 s[24:25], s61, v156
	v_cmp_gt_f32_e64 s[26:27], s61, v157
	v_cmp_gt_f32_e64 s[28:29], s61, v158
	v_cmp_gt_f32_e64 s[34:35], s61, v159
	v_cndmask_b32_e64 v180, 0, v102, s[24:25]
	v_cndmask_b32_e64 v181, 0, v102, s[26:27]
	v_cndmask_b32_e64 v182, 0, v102, s[28:29]
	v_cndmask_b32_e64 v183, 0, v102, s[34:35]
	v_add_f32_e32 v156, v156, v180
	v_add_f32_e32 v157, v157, v181
	v_add_f32_e32 v158, v158, v182
	v_add_f32_e32 v159, v159, v183
	v_exp_f32_e32 v156, v156
	v_exp_f32_e32 v157, v157
	v_exp_f32_e32 v158, v158
	v_exp_f32_e32 v159, v159
	v_cndmask_b32_e64 v180, 0, v103, s[24:25]
	v_cndmask_b32_e64 v181, 0, v103, s[26:27]
	v_cndmask_b32_e64 v182, 0, v103, s[28:29]
	v_cndmask_b32_e64 v183, 0, v103, s[34:35]
	v_ldexp_f32 v156, v156, v180
	v_ldexp_f32 v157, v157, v181
	v_ldexp_f32 v158, v158, v182
	v_ldexp_f32 v159, v159, v183
	v_add_f32_e32 v249, v249, v156
	v_add_f32_e32 v249, v249, v157
	v_add_f32_e32 v249, v249, v158
	v_add_f32_e32 v249, v249, v159
	v_sub_f32_e32 v160, v160, v248
	v_sub_f32_e32 v161, v161, v248
	v_sub_f32_e32 v162, v162, v248
	v_sub_f32_e32 v163, v163, v248
	v_cmp_gt_f32_e64 s[24:25], s61, v160
	v_cmp_gt_f32_e64 s[26:27], s61, v161
	v_cmp_gt_f32_e64 s[28:29], s61, v162
	v_cmp_gt_f32_e64 s[34:35], s61, v163
	v_cndmask_b32_e64 v180, 0, v102, s[24:25]
	v_cndmask_b32_e64 v181, 0, v102, s[26:27]
	v_cndmask_b32_e64 v182, 0, v102, s[28:29]
	v_cndmask_b32_e64 v183, 0, v102, s[34:35]
	v_add_f32_e32 v160, v160, v180
	v_add_f32_e32 v161, v161, v181
	v_add_f32_e32 v162, v162, v182
	v_add_f32_e32 v163, v163, v183
	v_exp_f32_e32 v160, v160
	v_exp_f32_e32 v161, v161
	v_exp_f32_e32 v162, v162
	v_exp_f32_e32 v163, v163
	v_cndmask_b32_e64 v180, 0, v103, s[24:25]
	v_cndmask_b32_e64 v181, 0, v103, s[26:27]
	v_cndmask_b32_e64 v182, 0, v103, s[28:29]
	v_cndmask_b32_e64 v183, 0, v103, s[34:35]
	v_ldexp_f32 v160, v160, v180
	v_ldexp_f32 v161, v161, v181
	v_ldexp_f32 v162, v162, v182
	v_ldexp_f32 v163, v163, v183
	v_add_f32_e32 v249, v249, v160
	v_add_f32_e32 v249, v249, v161
	v_add_f32_e32 v249, v249, v162
	v_add_f32_e32 v249, v249, v163
	v_sub_f32_e32 v164, v164, v248
	v_sub_f32_e32 v165, v165, v248
	v_sub_f32_e32 v166, v166, v248
	v_sub_f32_e32 v167, v167, v248
	v_cmp_gt_f32_e64 s[24:25], s61, v164
	v_cmp_gt_f32_e64 s[26:27], s61, v165
	v_cmp_gt_f32_e64 s[28:29], s61, v166
	v_cmp_gt_f32_e64 s[34:35], s61, v167
	v_cndmask_b32_e64 v180, 0, v102, s[24:25]
	v_cndmask_b32_e64 v181, 0, v102, s[26:27]
	v_cndmask_b32_e64 v182, 0, v102, s[28:29]
	v_cndmask_b32_e64 v183, 0, v102, s[34:35]
	v_add_f32_e32 v164, v164, v180
	v_add_f32_e32 v165, v165, v181
	v_add_f32_e32 v166, v166, v182
	v_add_f32_e32 v167, v167, v183
	v_exp_f32_e32 v164, v164
	v_exp_f32_e32 v165, v165
	v_exp_f32_e32 v166, v166
	v_exp_f32_e32 v167, v167
	v_cndmask_b32_e64 v180, 0, v103, s[24:25]
	v_cndmask_b32_e64 v181, 0, v103, s[26:27]
	v_cndmask_b32_e64 v182, 0, v103, s[28:29]
	v_cndmask_b32_e64 v183, 0, v103, s[34:35]
	v_ldexp_f32 v164, v164, v180
	v_ldexp_f32 v165, v165, v181
	v_ldexp_f32 v166, v166, v182
	v_ldexp_f32 v167, v167, v183
	v_add_f32_e32 v249, v249, v164
	v_add_f32_e32 v249, v249, v165
	v_add_f32_e32 v249, v249, v166
	v_add_f32_e32 v249, v249, v167
	v_sub_f32_e32 v168, v168, v248
	v_sub_f32_e32 v169, v169, v248
	v_sub_f32_e32 v170, v170, v248
	v_sub_f32_e32 v171, v171, v248
	v_cmp_gt_f32_e64 s[24:25], s61, v168
	v_cmp_gt_f32_e64 s[26:27], s61, v169
	v_cmp_gt_f32_e64 s[28:29], s61, v170
	v_cmp_gt_f32_e64 s[34:35], s61, v171
	v_cndmask_b32_e64 v180, 0, v102, s[24:25]
	v_cndmask_b32_e64 v181, 0, v102, s[26:27]
	v_cndmask_b32_e64 v182, 0, v102, s[28:29]
	v_cndmask_b32_e64 v183, 0, v102, s[34:35]
	v_add_f32_e32 v168, v168, v180
	v_add_f32_e32 v169, v169, v181
	v_add_f32_e32 v170, v170, v182
	v_add_f32_e32 v171, v171, v183
	v_exp_f32_e32 v168, v168
	v_exp_f32_e32 v169, v169
	v_exp_f32_e32 v170, v170
	v_exp_f32_e32 v171, v171
	v_cndmask_b32_e64 v180, 0, v103, s[24:25]
	v_cndmask_b32_e64 v181, 0, v103, s[26:27]
	v_cndmask_b32_e64 v182, 0, v103, s[28:29]
	v_cndmask_b32_e64 v183, 0, v103, s[34:35]
	v_ldexp_f32 v168, v168, v180
	v_ldexp_f32 v169, v169, v181
	v_ldexp_f32 v170, v170, v182
	v_ldexp_f32 v171, v171, v183
	v_add_f32_e32 v249, v249, v168
	v_add_f32_e32 v249, v249, v169
	v_add_f32_e32 v249, v249, v170
	v_add_f32_e32 v249, v249, v171
	v_sub_f32_e32 v172, v172, v248
	v_sub_f32_e32 v173, v173, v248
	v_sub_f32_e32 v174, v174, v248
	v_sub_f32_e32 v175, v175, v248
	v_cmp_gt_f32_e64 s[24:25], s61, v172
	v_cmp_gt_f32_e64 s[26:27], s61, v173
	v_cmp_gt_f32_e64 s[28:29], s61, v174
	v_cmp_gt_f32_e64 s[34:35], s61, v175
	v_cndmask_b32_e64 v180, 0, v102, s[24:25]
	v_cndmask_b32_e64 v181, 0, v102, s[26:27]
	v_cndmask_b32_e64 v182, 0, v102, s[28:29]
	v_cndmask_b32_e64 v183, 0, v102, s[34:35]
	v_add_f32_e32 v172, v172, v180
	v_add_f32_e32 v173, v173, v181
	v_add_f32_e32 v174, v174, v182
	v_add_f32_e32 v175, v175, v183
	v_exp_f32_e32 v172, v172
	v_exp_f32_e32 v173, v173
	v_exp_f32_e32 v174, v174
	v_exp_f32_e32 v175, v175
	v_cndmask_b32_e64 v180, 0, v103, s[24:25]
	v_cndmask_b32_e64 v181, 0, v103, s[26:27]
	v_cndmask_b32_e64 v182, 0, v103, s[28:29]
	v_cndmask_b32_e64 v183, 0, v103, s[34:35]
	v_ldexp_f32 v172, v172, v180
	v_ldexp_f32 v173, v173, v181
	v_ldexp_f32 v174, v174, v182
	v_ldexp_f32 v175, v175, v183
	v_add_f32_e32 v249, v249, v172
	v_add_f32_e32 v249, v249, v173
	v_add_f32_e32 v249, v249, v174
	v_add_f32_e32 v249, v249, v175
	v_sub_f32_e32 v176, v176, v248
	v_sub_f32_e32 v177, v177, v248
	v_sub_f32_e32 v178, v178, v248
	v_sub_f32_e32 v179, v179, v248
	v_cmp_gt_f32_e64 s[24:25], s61, v176
	v_cmp_gt_f32_e64 s[26:27], s61, v177
	v_cmp_gt_f32_e64 s[28:29], s61, v178
	v_cmp_gt_f32_e64 s[34:35], s61, v179
	v_cndmask_b32_e64 v180, 0, v102, s[24:25]
	v_cndmask_b32_e64 v181, 0, v102, s[26:27]
	v_cndmask_b32_e64 v182, 0, v102, s[28:29]
	v_cndmask_b32_e64 v183, 0, v102, s[34:35]
	v_add_f32_e32 v176, v176, v180
	v_add_f32_e32 v177, v177, v181
	v_add_f32_e32 v178, v178, v182
	v_add_f32_e32 v179, v179, v183
	v_exp_f32_e32 v176, v176
	v_exp_f32_e32 v177, v177
	v_exp_f32_e32 v178, v178
	v_exp_f32_e32 v179, v179
	v_cndmask_b32_e64 v180, 0, v103, s[24:25]
	v_cndmask_b32_e64 v181, 0, v103, s[26:27]
	v_cndmask_b32_e64 v182, 0, v103, s[28:29]
	v_cndmask_b32_e64 v183, 0, v103, s[34:35]
	v_ldexp_f32 v176, v176, v180
	v_ldexp_f32 v177, v177, v181
	v_ldexp_f32 v178, v178, v182
	v_ldexp_f32 v179, v179, v183
	v_add_f32_e32 v249, v249, v176
	v_add_f32_e32 v249, v249, v177
	v_add_f32_e32 v249, v249, v178
	v_add_f32_e32 v249, v249, v179
	ds_write_b32 v81, v249 offset:51216
	v_mov_b32_e32 v180, 0
	v_mov_b32_e32 v181, 0
	v_mov_b32_e32 v182, 0
	v_mov_b32_e32 v183, 0
	v_mov_b32_e32 v184, 0
	v_mov_b32_e32 v185, 0
	v_mov_b32_e32 v186, 0
	v_mov_b32_e32 v187, 0
	v_mov_b32_e32 v188, 0
	v_mov_b32_e32 v189, 0
	v_mov_b32_e32 v190, 0
	v_mov_b32_e32 v191, 0
	v_mov_b32_e32 v192, 0
	v_mov_b32_e32 v193, 0
	v_mov_b32_e32 v194, 0
	v_mov_b32_e32 v195, 0
	v_and_b32_e32 v15, 63, v0
	v_lshlrev_b32_e32 v15, 4, v15
	v_add_u32_e32 v105, s73, v15
	v_xor_b32_e32 v106, 64, v105
	v_lshlrev_b32_e32 v15, 10, v76
	v_lshl_add_u32 v15, v77, 2, v15
	v_and_b32_e32 v78, 1, v76
	v_lshl_add_u32 v15, v78, 6, v15
	v_add_u32_e32 v109, s73, v15
	v_xor_b32_e32 v110, 64, v109
	v_add_u32_e32 v111, 0x80, v109
	v_add_u32_e32 v14, 0x80, v110
	s_waitcnt vmcnt(8)
	ds_write_b128 v105, v[16:19]
	ds_write_b128 v106, v[20:23] offset:1024
	ds_write_b128 v105, v[24:27] offset:2048
	ds_write_b128 v106, v[28:31] offset:3072
	ds_write_b128 v105, v[32:35] offset:4096
	ds_write_b128 v106, v[36:39] offset:5120
	ds_write_b128 v105, v[40:43] offset:6144
	ds_write_b128 v106, v[44:47] offset:7168
	global_load_dwordx4 v[16:19], v72, s[76:77] nt
	global_load_dwordx4 v[20:23], v73, s[76:77] nt
	global_load_dwordx4 v[24:27], v74, s[76:77] nt
	global_load_dwordx4 v[28:31], v75, s[76:77] nt
	global_load_dwordx4 v[32:35], v72, s[78:79] nt
	global_load_dwordx4 v[36:39], v73, s[78:79] nt
	global_load_dwordx4 v[40:43], v74, s[78:79] nt
	global_load_dwordx4 v[44:47], v75, s[78:79] nt
	s_add_u32 s76, s76, 0x80000
	s_addc_u32 s77, s77, 0
	s_add_u32 s78, s78, 0x80000
	s_addc_u32 s79, s79, 0
	v_cvt_pk_bf16_f32 v10, v112, v113
	v_cvt_pk_bf16_f32 v11, v114, v115
	v_cvt_pk_bf16_f32 v12, v116, v117
	v_cvt_pk_bf16_f32 v13, v118, v119
	ds_read2st64_b32 v[2:3], v109 offset0:0 offset1:1
	ds_read2st64_b32 v[4:5], v109 offset0:2 offset1:3
	ds_read2st64_b32 v[6:7], v109 offset0:16 offset1:17
	ds_read2st64_b32 v[8:9], v109 offset0:18 offset1:19
	s_waitcnt lgkmcnt(0)
	v_cvt_pk_bf16_f32 v250, v2, v3
	v_cvt_pk_bf16_f32 v251, v4, v5
	v_cvt_pk_bf16_f32 v252, v6, v7
	v_cvt_pk_bf16_f32 v253, v8, v9
	s_nop 1
	v_mfma_f32_16x16x32_bf16 v[180:183], v[250:253], v[10:13], v[180:183]
	ds_read2st64_b32 v[2:3], v110 offset0:0 offset1:1
	ds_read2st64_b32 v[4:5], v110 offset0:2 offset1:3
	ds_read2st64_b32 v[6:7], v110 offset0:16 offset1:17
	ds_read2st64_b32 v[8:9], v110 offset0:18 offset1:19
	s_waitcnt lgkmcnt(0)
	v_cvt_pk_bf16_f32 v250, v2, v3
	v_cvt_pk_bf16_f32 v251, v4, v5
	v_cvt_pk_bf16_f32 v252, v6, v7
	v_cvt_pk_bf16_f32 v253, v8, v9
	s_nop 1
	v_mfma_f32_16x16x32_bf16 v[184:187], v[250:253], v[10:13], v[184:187]
	ds_read2st64_b32 v[2:3], v111 offset0:0 offset1:1
	ds_read2st64_b32 v[4:5], v111 offset0:2 offset1:3
	ds_read2st64_b32 v[6:7], v111 offset0:16 offset1:17
	ds_read2st64_b32 v[8:9], v111 offset0:18 offset1:19
	s_waitcnt lgkmcnt(0)
	v_cvt_pk_bf16_f32 v250, v2, v3
	v_cvt_pk_bf16_f32 v251, v4, v5
	v_cvt_pk_bf16_f32 v252, v6, v7
	v_cvt_pk_bf16_f32 v253, v8, v9
	s_nop 1
	v_mfma_f32_16x16x32_bf16 v[188:191], v[250:253], v[10:13], v[188:191]
	ds_read2st64_b32 v[2:3], v14 offset0:0 offset1:1
	ds_read2st64_b32 v[4:5], v14 offset0:2 offset1:3
	ds_read2st64_b32 v[6:7], v14 offset0:16 offset1:17
	ds_read2st64_b32 v[8:9], v14 offset0:18 offset1:19
	s_waitcnt lgkmcnt(0)
	v_cvt_pk_bf16_f32 v250, v2, v3
	v_cvt_pk_bf16_f32 v251, v4, v5
	v_cvt_pk_bf16_f32 v252, v6, v7
	v_cvt_pk_bf16_f32 v253, v8, v9
	s_nop 1
	v_mfma_f32_16x16x32_bf16 v[192:195], v[250:253], v[10:13], v[192:195]
	s_waitcnt vmcnt(8)
	ds_write_b128 v105, v[48:51]
	ds_write_b128 v106, v[52:55] offset:1024
	ds_write_b128 v105, v[56:59] offset:2048
	ds_write_b128 v106, v[60:63] offset:3072
	ds_write_b128 v105, v[200:203] offset:4096
	ds_write_b128 v106, v[204:207] offset:5120
	ds_write_b128 v105, v[208:211] offset:6144
	ds_write_b128 v106, v[212:215] offset:7168
	global_load_dwordx4 v[48:51], v72, s[76:77] nt
	global_load_dwordx4 v[52:55], v73, s[76:77] nt
	global_load_dwordx4 v[56:59], v74, s[76:77] nt
	global_load_dwordx4 v[60:63], v75, s[76:77] nt
	global_load_dwordx4 v[200:203], v72, s[78:79] nt
	global_load_dwordx4 v[204:207], v73, s[78:79] nt
	global_load_dwordx4 v[208:211], v74, s[78:79] nt
	global_load_dwordx4 v[212:215], v75, s[78:79] nt
	s_add_u32 s76, s76, 0x80000
	s_addc_u32 s77, s77, 0
	s_add_u32 s78, s78, 0x80000
	s_addc_u32 s79, s79, 0
	v_cvt_pk_bf16_f32 v10, v120, v121
	v_cvt_pk_bf16_f32 v11, v122, v123
	v_cvt_pk_bf16_f32 v12, v124, v125
	v_cvt_pk_bf16_f32 v13, v126, v127
	ds_read2st64_b32 v[2:3], v109 offset0:0 offset1:1
	ds_read2st64_b32 v[4:5], v109 offset0:2 offset1:3
	ds_read2st64_b32 v[6:7], v109 offset0:16 offset1:17
	ds_read2st64_b32 v[8:9], v109 offset0:18 offset1:19
	s_waitcnt lgkmcnt(0)
	v_cvt_pk_bf16_f32 v250, v2, v3
	v_cvt_pk_bf16_f32 v251, v4, v5
	v_cvt_pk_bf16_f32 v252, v6, v7
	v_cvt_pk_bf16_f32 v253, v8, v9
	s_nop 1
	v_mfma_f32_16x16x32_bf16 v[180:183], v[250:253], v[10:13], v[180:183]
	ds_read2st64_b32 v[2:3], v110 offset0:0 offset1:1
	ds_read2st64_b32 v[4:5], v110 offset0:2 offset1:3
	ds_read2st64_b32 v[6:7], v110 offset0:16 offset1:17
	ds_read2st64_b32 v[8:9], v110 offset0:18 offset1:19
	s_waitcnt lgkmcnt(0)
	v_cvt_pk_bf16_f32 v250, v2, v3
	v_cvt_pk_bf16_f32 v251, v4, v5
	v_cvt_pk_bf16_f32 v252, v6, v7
	v_cvt_pk_bf16_f32 v253, v8, v9
	s_nop 1
	v_mfma_f32_16x16x32_bf16 v[184:187], v[250:253], v[10:13], v[184:187]
	ds_read2st64_b32 v[2:3], v111 offset0:0 offset1:1
	ds_read2st64_b32 v[4:5], v111 offset0:2 offset1:3
	ds_read2st64_b32 v[6:7], v111 offset0:16 offset1:17
	ds_read2st64_b32 v[8:9], v111 offset0:18 offset1:19
	s_waitcnt lgkmcnt(0)
	v_cvt_pk_bf16_f32 v250, v2, v3
	v_cvt_pk_bf16_f32 v251, v4, v5
	v_cvt_pk_bf16_f32 v252, v6, v7
	v_cvt_pk_bf16_f32 v253, v8, v9
	s_nop 1
	v_mfma_f32_16x16x32_bf16 v[188:191], v[250:253], v[10:13], v[188:191]
	ds_read2st64_b32 v[2:3], v14 offset0:0 offset1:1
	ds_read2st64_b32 v[4:5], v14 offset0:2 offset1:3
	ds_read2st64_b32 v[6:7], v14 offset0:16 offset1:17
	ds_read2st64_b32 v[8:9], v14 offset0:18 offset1:19
	s_waitcnt lgkmcnt(0)
	v_cvt_pk_bf16_f32 v250, v2, v3
	v_cvt_pk_bf16_f32 v251, v4, v5
	v_cvt_pk_bf16_f32 v252, v6, v7
	v_cvt_pk_bf16_f32 v253, v8, v9
	s_nop 1
	v_mfma_f32_16x16x32_bf16 v[192:195], v[250:253], v[10:13], v[192:195]
	s_waitcnt vmcnt(8)
	ds_write_b128 v105, v[16:19]
	ds_write_b128 v106, v[20:23] offset:1024
	ds_write_b128 v105, v[24:27] offset:2048
	ds_write_b128 v106, v[28:31] offset:3072
	ds_write_b128 v105, v[32:35] offset:4096
	ds_write_b128 v106, v[36:39] offset:5120
	ds_write_b128 v105, v[40:43] offset:6144
	ds_write_b128 v106, v[44:47] offset:7168
	global_load_dwordx4 v[16:19], v72, s[76:77] nt
	global_load_dwordx4 v[20:23], v73, s[76:77] nt
	global_load_dwordx4 v[24:27], v74, s[76:77] nt
	global_load_dwordx4 v[28:31], v75, s[76:77] nt
	global_load_dwordx4 v[32:35], v72, s[78:79] nt
	global_load_dwordx4 v[36:39], v73, s[78:79] nt
	global_load_dwordx4 v[40:43], v74, s[78:79] nt
	global_load_dwordx4 v[44:47], v75, s[78:79] nt
	s_add_u32 s76, s76, 0x80000
	s_addc_u32 s77, s77, 0
	s_add_u32 s78, s78, 0x80000
	s_addc_u32 s79, s79, 0
	v_cvt_pk_bf16_f32 v10, v128, v129
	v_cvt_pk_bf16_f32 v11, v130, v131
	v_cvt_pk_bf16_f32 v12, v132, v133
	v_cvt_pk_bf16_f32 v13, v134, v135
	ds_read2st64_b32 v[2:3], v109 offset0:0 offset1:1
	ds_read2st64_b32 v[4:5], v109 offset0:2 offset1:3
	ds_read2st64_b32 v[6:7], v109 offset0:16 offset1:17
	ds_read2st64_b32 v[8:9], v109 offset0:18 offset1:19
	s_waitcnt lgkmcnt(0)
	v_cvt_pk_bf16_f32 v250, v2, v3
	v_cvt_pk_bf16_f32 v251, v4, v5
	v_cvt_pk_bf16_f32 v252, v6, v7
	v_cvt_pk_bf16_f32 v253, v8, v9
	s_nop 1
	v_mfma_f32_16x16x32_bf16 v[180:183], v[250:253], v[10:13], v[180:183]
	ds_read2st64_b32 v[2:3], v110 offset0:0 offset1:1
	ds_read2st64_b32 v[4:5], v110 offset0:2 offset1:3
	ds_read2st64_b32 v[6:7], v110 offset0:16 offset1:17
	ds_read2st64_b32 v[8:9], v110 offset0:18 offset1:19
	s_waitcnt lgkmcnt(0)
	v_cvt_pk_bf16_f32 v250, v2, v3
	v_cvt_pk_bf16_f32 v251, v4, v5
	v_cvt_pk_bf16_f32 v252, v6, v7
	v_cvt_pk_bf16_f32 v253, v8, v9
	s_nop 1
	v_mfma_f32_16x16x32_bf16 v[184:187], v[250:253], v[10:13], v[184:187]
	ds_read2st64_b32 v[2:3], v111 offset0:0 offset1:1
	ds_read2st64_b32 v[4:5], v111 offset0:2 offset1:3
	ds_read2st64_b32 v[6:7], v111 offset0:16 offset1:17
	ds_read2st64_b32 v[8:9], v111 offset0:18 offset1:19
	s_waitcnt lgkmcnt(0)
	v_cvt_pk_bf16_f32 v250, v2, v3
	v_cvt_pk_bf16_f32 v251, v4, v5
	v_cvt_pk_bf16_f32 v252, v6, v7
	v_cvt_pk_bf16_f32 v253, v8, v9
	s_nop 1
	v_mfma_f32_16x16x32_bf16 v[188:191], v[250:253], v[10:13], v[188:191]
	ds_read2st64_b32 v[2:3], v14 offset0:0 offset1:1
	ds_read2st64_b32 v[4:5], v14 offset0:2 offset1:3
	ds_read2st64_b32 v[6:7], v14 offset0:16 offset1:17
	ds_read2st64_b32 v[8:9], v14 offset0:18 offset1:19
	s_waitcnt lgkmcnt(0)
	v_cvt_pk_bf16_f32 v250, v2, v3
	v_cvt_pk_bf16_f32 v251, v4, v5
	v_cvt_pk_bf16_f32 v252, v6, v7
	v_cvt_pk_bf16_f32 v253, v8, v9
	s_nop 1
	v_mfma_f32_16x16x32_bf16 v[192:195], v[250:253], v[10:13], v[192:195]
	s_waitcnt vmcnt(8)
	ds_write_b128 v105, v[48:51]
	ds_write_b128 v106, v[52:55] offset:1024
	ds_write_b128 v105, v[56:59] offset:2048
	ds_write_b128 v106, v[60:63] offset:3072
	ds_write_b128 v105, v[200:203] offset:4096
	ds_write_b128 v106, v[204:207] offset:5120
	ds_write_b128 v105, v[208:211] offset:6144
	ds_write_b128 v106, v[212:215] offset:7168
	global_load_dwordx4 v[48:51], v72, s[76:77] nt
	global_load_dwordx4 v[52:55], v73, s[76:77] nt
	global_load_dwordx4 v[56:59], v74, s[76:77] nt
	global_load_dwordx4 v[60:63], v75, s[76:77] nt
	global_load_dwordx4 v[200:203], v72, s[78:79] nt
	global_load_dwordx4 v[204:207], v73, s[78:79] nt
	global_load_dwordx4 v[208:211], v74, s[78:79] nt
	global_load_dwordx4 v[212:215], v75, s[78:79] nt
	s_add_u32 s76, s76, 0x80000
	s_addc_u32 s77, s77, 0
	s_add_u32 s78, s78, 0x80000
	s_addc_u32 s79, s79, 0
	v_cvt_pk_bf16_f32 v10, v136, v137
	v_cvt_pk_bf16_f32 v11, v138, v139
	v_cvt_pk_bf16_f32 v12, v140, v141
	v_cvt_pk_bf16_f32 v13, v142, v143
	ds_read2st64_b32 v[2:3], v109 offset0:0 offset1:1
	ds_read2st64_b32 v[4:5], v109 offset0:2 offset1:3
	ds_read2st64_b32 v[6:7], v109 offset0:16 offset1:17
	ds_read2st64_b32 v[8:9], v109 offset0:18 offset1:19
	s_waitcnt lgkmcnt(0)
	v_cvt_pk_bf16_f32 v250, v2, v3
	v_cvt_pk_bf16_f32 v251, v4, v5
	v_cvt_pk_bf16_f32 v252, v6, v7
	v_cvt_pk_bf16_f32 v253, v8, v9
	s_nop 1
	v_mfma_f32_16x16x32_bf16 v[180:183], v[250:253], v[10:13], v[180:183]
	ds_read2st64_b32 v[2:3], v110 offset0:0 offset1:1
	ds_read2st64_b32 v[4:5], v110 offset0:2 offset1:3
	ds_read2st64_b32 v[6:7], v110 offset0:16 offset1:17
	ds_read2st64_b32 v[8:9], v110 offset0:18 offset1:19
	s_waitcnt lgkmcnt(0)
	v_cvt_pk_bf16_f32 v250, v2, v3
	v_cvt_pk_bf16_f32 v251, v4, v5
	v_cvt_pk_bf16_f32 v252, v6, v7
	v_cvt_pk_bf16_f32 v253, v8, v9
	s_nop 1
	v_mfma_f32_16x16x32_bf16 v[184:187], v[250:253], v[10:13], v[184:187]
	ds_read2st64_b32 v[2:3], v111 offset0:0 offset1:1
	ds_read2st64_b32 v[4:5], v111 offset0:2 offset1:3
	ds_read2st64_b32 v[6:7], v111 offset0:16 offset1:17
	ds_read2st64_b32 v[8:9], v111 offset0:18 offset1:19
	s_waitcnt lgkmcnt(0)
	v_cvt_pk_bf16_f32 v250, v2, v3
	v_cvt_pk_bf16_f32 v251, v4, v5
	v_cvt_pk_bf16_f32 v252, v6, v7
	v_cvt_pk_bf16_f32 v253, v8, v9
	s_nop 1
	v_mfma_f32_16x16x32_bf16 v[188:191], v[250:253], v[10:13], v[188:191]
	ds_read2st64_b32 v[2:3], v14 offset0:0 offset1:1
	ds_read2st64_b32 v[4:5], v14 offset0:2 offset1:3
	ds_read2st64_b32 v[6:7], v14 offset0:16 offset1:17
	ds_read2st64_b32 v[8:9], v14 offset0:18 offset1:19
	s_waitcnt lgkmcnt(0)
	v_cvt_pk_bf16_f32 v250, v2, v3
	v_cvt_pk_bf16_f32 v251, v4, v5
	v_cvt_pk_bf16_f32 v252, v6, v7
	v_cvt_pk_bf16_f32 v253, v8, v9
	s_nop 1
	v_mfma_f32_16x16x32_bf16 v[192:195], v[250:253], v[10:13], v[192:195]
	s_waitcnt vmcnt(8)
	ds_write_b128 v105, v[16:19]
	ds_write_b128 v106, v[20:23] offset:1024
	ds_write_b128 v105, v[24:27] offset:2048
	ds_write_b128 v106, v[28:31] offset:3072
	ds_write_b128 v105, v[32:35] offset:4096
	ds_write_b128 v106, v[36:39] offset:5120
	ds_write_b128 v105, v[40:43] offset:6144
	ds_write_b128 v106, v[44:47] offset:7168
	global_load_dwordx4 v[16:19], v72, s[76:77] nt
	global_load_dwordx4 v[20:23], v73, s[76:77] nt
	global_load_dwordx4 v[24:27], v74, s[76:77] nt
	global_load_dwordx4 v[28:31], v75, s[76:77] nt
	global_load_dwordx4 v[32:35], v72, s[78:79] nt
	global_load_dwordx4 v[36:39], v73, s[78:79] nt
	global_load_dwordx4 v[40:43], v74, s[78:79] nt
	global_load_dwordx4 v[44:47], v75, s[78:79] nt
	s_add_u32 s76, s76, 0x80000
	s_addc_u32 s77, s77, 0
	s_add_u32 s78, s78, 0x80000
	s_addc_u32 s79, s79, 0
	v_cvt_pk_bf16_f32 v10, v144, v145
	v_cvt_pk_bf16_f32 v11, v146, v147
	v_cvt_pk_bf16_f32 v12, v148, v149
	v_cvt_pk_bf16_f32 v13, v150, v151
	ds_read2st64_b32 v[2:3], v109 offset0:0 offset1:1
	ds_read2st64_b32 v[4:5], v109 offset0:2 offset1:3
	ds_read2st64_b32 v[6:7], v109 offset0:16 offset1:17
	ds_read2st64_b32 v[8:9], v109 offset0:18 offset1:19
	s_waitcnt lgkmcnt(0)
	v_cvt_pk_bf16_f32 v250, v2, v3
	v_cvt_pk_bf16_f32 v251, v4, v5
	v_cvt_pk_bf16_f32 v252, v6, v7
	v_cvt_pk_bf16_f32 v253, v8, v9
	s_nop 1
	v_mfma_f32_16x16x32_bf16 v[180:183], v[250:253], v[10:13], v[180:183]
	ds_read2st64_b32 v[2:3], v110 offset0:0 offset1:1
	ds_read2st64_b32 v[4:5], v110 offset0:2 offset1:3
	ds_read2st64_b32 v[6:7], v110 offset0:16 offset1:17
	ds_read2st64_b32 v[8:9], v110 offset0:18 offset1:19
	s_waitcnt lgkmcnt(0)
	v_cvt_pk_bf16_f32 v250, v2, v3
	v_cvt_pk_bf16_f32 v251, v4, v5
	v_cvt_pk_bf16_f32 v252, v6, v7
	v_cvt_pk_bf16_f32 v253, v8, v9
	s_nop 1
	v_mfma_f32_16x16x32_bf16 v[184:187], v[250:253], v[10:13], v[184:187]
	ds_read2st64_b32 v[2:3], v111 offset0:0 offset1:1
	ds_read2st64_b32 v[4:5], v111 offset0:2 offset1:3
	ds_read2st64_b32 v[6:7], v111 offset0:16 offset1:17
	ds_read2st64_b32 v[8:9], v111 offset0:18 offset1:19
	s_waitcnt lgkmcnt(0)
	v_cvt_pk_bf16_f32 v250, v2, v3
	v_cvt_pk_bf16_f32 v251, v4, v5
	v_cvt_pk_bf16_f32 v252, v6, v7
	v_cvt_pk_bf16_f32 v253, v8, v9
	s_nop 1
	v_mfma_f32_16x16x32_bf16 v[188:191], v[250:253], v[10:13], v[188:191]
	ds_read2st64_b32 v[2:3], v14 offset0:0 offset1:1
	ds_read2st64_b32 v[4:5], v14 offset0:2 offset1:3
	ds_read2st64_b32 v[6:7], v14 offset0:16 offset1:17
	ds_read2st64_b32 v[8:9], v14 offset0:18 offset1:19
	s_waitcnt lgkmcnt(0)
	v_cvt_pk_bf16_f32 v250, v2, v3
	v_cvt_pk_bf16_f32 v251, v4, v5
	v_cvt_pk_bf16_f32 v252, v6, v7
	v_cvt_pk_bf16_f32 v253, v8, v9
	s_nop 1
	v_mfma_f32_16x16x32_bf16 v[192:195], v[250:253], v[10:13], v[192:195]
	s_waitcnt vmcnt(8)
	ds_write_b128 v105, v[48:51]
	ds_write_b128 v106, v[52:55] offset:1024
	ds_write_b128 v105, v[56:59] offset:2048
	ds_write_b128 v106, v[60:63] offset:3072
	ds_write_b128 v105, v[200:203] offset:4096
	ds_write_b128 v106, v[204:207] offset:5120
	ds_write_b128 v105, v[208:211] offset:6144
	ds_write_b128 v106, v[212:215] offset:7168
	global_load_dwordx4 v[48:51], v72, s[76:77] nt
	global_load_dwordx4 v[52:55], v73, s[76:77] nt
	global_load_dwordx4 v[56:59], v74, s[76:77] nt
	global_load_dwordx4 v[60:63], v75, s[76:77] nt
	global_load_dwordx4 v[200:203], v72, s[78:79] nt
	global_load_dwordx4 v[204:207], v73, s[78:79] nt
	global_load_dwordx4 v[208:211], v74, s[78:79] nt
	global_load_dwordx4 v[212:215], v75, s[78:79] nt
	s_add_u32 s76, s76, 0x80000
	s_addc_u32 s77, s77, 0
	s_add_u32 s78, s78, 0x80000
	s_addc_u32 s79, s79, 0
	v_cvt_pk_bf16_f32 v10, v152, v153
	v_cvt_pk_bf16_f32 v11, v154, v155
	v_cvt_pk_bf16_f32 v12, v156, v157
	v_cvt_pk_bf16_f32 v13, v158, v159
	ds_read2st64_b32 v[2:3], v109 offset0:0 offset1:1
	ds_read2st64_b32 v[4:5], v109 offset0:2 offset1:3
	ds_read2st64_b32 v[6:7], v109 offset0:16 offset1:17
	ds_read2st64_b32 v[8:9], v109 offset0:18 offset1:19
	s_waitcnt lgkmcnt(0)
	v_cvt_pk_bf16_f32 v250, v2, v3
	v_cvt_pk_bf16_f32 v251, v4, v5
	v_cvt_pk_bf16_f32 v252, v6, v7
	v_cvt_pk_bf16_f32 v253, v8, v9
	s_nop 1
	v_mfma_f32_16x16x32_bf16 v[180:183], v[250:253], v[10:13], v[180:183]
	ds_read2st64_b32 v[2:3], v110 offset0:0 offset1:1
	ds_read2st64_b32 v[4:5], v110 offset0:2 offset1:3
	ds_read2st64_b32 v[6:7], v110 offset0:16 offset1:17
	ds_read2st64_b32 v[8:9], v110 offset0:18 offset1:19
	s_waitcnt lgkmcnt(0)
	v_cvt_pk_bf16_f32 v250, v2, v3
	v_cvt_pk_bf16_f32 v251, v4, v5
	v_cvt_pk_bf16_f32 v252, v6, v7
	v_cvt_pk_bf16_f32 v253, v8, v9
	s_nop 1
	v_mfma_f32_16x16x32_bf16 v[184:187], v[250:253], v[10:13], v[184:187]
	ds_read2st64_b32 v[2:3], v111 offset0:0 offset1:1
	ds_read2st64_b32 v[4:5], v111 offset0:2 offset1:3
	ds_read2st64_b32 v[6:7], v111 offset0:16 offset1:17
	ds_read2st64_b32 v[8:9], v111 offset0:18 offset1:19
	s_waitcnt lgkmcnt(0)
	v_cvt_pk_bf16_f32 v250, v2, v3
	v_cvt_pk_bf16_f32 v251, v4, v5
	v_cvt_pk_bf16_f32 v252, v6, v7
	v_cvt_pk_bf16_f32 v253, v8, v9
	s_nop 1
	v_mfma_f32_16x16x32_bf16 v[188:191], v[250:253], v[10:13], v[188:191]
	ds_read2st64_b32 v[2:3], v14 offset0:0 offset1:1
	ds_read2st64_b32 v[4:5], v14 offset0:2 offset1:3
	ds_read2st64_b32 v[6:7], v14 offset0:16 offset1:17
	ds_read2st64_b32 v[8:9], v14 offset0:18 offset1:19
	s_waitcnt lgkmcnt(0)
	v_cvt_pk_bf16_f32 v250, v2, v3
	v_cvt_pk_bf16_f32 v251, v4, v5
	v_cvt_pk_bf16_f32 v252, v6, v7
	v_cvt_pk_bf16_f32 v253, v8, v9
	s_nop 1
	v_mfma_f32_16x16x32_bf16 v[192:195], v[250:253], v[10:13], v[192:195]
	s_waitcnt vmcnt(8)
	ds_write_b128 v105, v[16:19]
	ds_write_b128 v106, v[20:23] offset:1024
	ds_write_b128 v105, v[24:27] offset:2048
	ds_write_b128 v106, v[28:31] offset:3072
	ds_write_b128 v105, v[32:35] offset:4096
	ds_write_b128 v106, v[36:39] offset:5120
	ds_write_b128 v105, v[40:43] offset:6144
	ds_write_b128 v106, v[44:47] offset:7168
	v_cvt_pk_bf16_f32 v10, v160, v161
	v_cvt_pk_bf16_f32 v11, v162, v163
	v_cvt_pk_bf16_f32 v12, v164, v165
	v_cvt_pk_bf16_f32 v13, v166, v167
	ds_read2st64_b32 v[2:3], v109 offset0:0 offset1:1
	ds_read2st64_b32 v[4:5], v109 offset0:2 offset1:3
	ds_read2st64_b32 v[6:7], v109 offset0:16 offset1:17
	ds_read2st64_b32 v[8:9], v109 offset0:18 offset1:19
	s_waitcnt lgkmcnt(0)
	v_cvt_pk_bf16_f32 v250, v2, v3
	v_cvt_pk_bf16_f32 v251, v4, v5
	v_cvt_pk_bf16_f32 v252, v6, v7
	v_cvt_pk_bf16_f32 v253, v8, v9
	s_nop 1
	v_mfma_f32_16x16x32_bf16 v[180:183], v[250:253], v[10:13], v[180:183]
	ds_read2st64_b32 v[2:3], v110 offset0:0 offset1:1
	ds_read2st64_b32 v[4:5], v110 offset0:2 offset1:3
	ds_read2st64_b32 v[6:7], v110 offset0:16 offset1:17
	ds_read2st64_b32 v[8:9], v110 offset0:18 offset1:19
	s_waitcnt lgkmcnt(0)
	v_cvt_pk_bf16_f32 v250, v2, v3
	v_cvt_pk_bf16_f32 v251, v4, v5
	v_cvt_pk_bf16_f32 v252, v6, v7
	v_cvt_pk_bf16_f32 v253, v8, v9
	s_nop 1
	v_mfma_f32_16x16x32_bf16 v[184:187], v[250:253], v[10:13], v[184:187]
	ds_read2st64_b32 v[2:3], v111 offset0:0 offset1:1
	ds_read2st64_b32 v[4:5], v111 offset0:2 offset1:3
	ds_read2st64_b32 v[6:7], v111 offset0:16 offset1:17
	ds_read2st64_b32 v[8:9], v111 offset0:18 offset1:19
	s_waitcnt lgkmcnt(0)
	v_cvt_pk_bf16_f32 v250, v2, v3
	v_cvt_pk_bf16_f32 v251, v4, v5
	v_cvt_pk_bf16_f32 v252, v6, v7
	v_cvt_pk_bf16_f32 v253, v8, v9
	s_nop 1
	v_mfma_f32_16x16x32_bf16 v[188:191], v[250:253], v[10:13], v[188:191]
	ds_read2st64_b32 v[2:3], v14 offset0:0 offset1:1
	ds_read2st64_b32 v[4:5], v14 offset0:2 offset1:3
	ds_read2st64_b32 v[6:7], v14 offset0:16 offset1:17
	ds_read2st64_b32 v[8:9], v14 offset0:18 offset1:19
	s_waitcnt lgkmcnt(0)
	v_cvt_pk_bf16_f32 v250, v2, v3
	v_cvt_pk_bf16_f32 v251, v4, v5
	v_cvt_pk_bf16_f32 v252, v6, v7
	v_cvt_pk_bf16_f32 v253, v8, v9
	s_nop 1
	v_mfma_f32_16x16x32_bf16 v[192:195], v[250:253], v[10:13], v[192:195]
	s_waitcnt vmcnt(0)
	ds_write_b128 v105, v[48:51]
	ds_write_b128 v106, v[52:55] offset:1024
	ds_write_b128 v105, v[56:59] offset:2048
	ds_write_b128 v106, v[60:63] offset:3072
	ds_write_b128 v105, v[200:203] offset:4096
	ds_write_b128 v106, v[204:207] offset:5120
	ds_write_b128 v105, v[208:211] offset:6144
	ds_write_b128 v106, v[212:215] offset:7168
	v_cvt_pk_bf16_f32 v10, v168, v169
	v_cvt_pk_bf16_f32 v11, v170, v171
	v_cvt_pk_bf16_f32 v12, v172, v173
	v_cvt_pk_bf16_f32 v13, v174, v175
	ds_read2st64_b32 v[2:3], v109 offset0:0 offset1:1
	ds_read2st64_b32 v[4:5], v109 offset0:2 offset1:3
	ds_read2st64_b32 v[6:7], v109 offset0:16 offset1:17
	ds_read2st64_b32 v[8:9], v109 offset0:18 offset1:19
	s_waitcnt lgkmcnt(0)
	v_cvt_pk_bf16_f32 v250, v2, v3
	v_cvt_pk_bf16_f32 v251, v4, v5
	v_cvt_pk_bf16_f32 v252, v6, v7
	v_cvt_pk_bf16_f32 v253, v8, v9
	s_nop 1
	v_mfma_f32_16x16x32_bf16 v[180:183], v[250:253], v[10:13], v[180:183]
	ds_read2st64_b32 v[2:3], v110 offset0:0 offset1:1
	ds_read2st64_b32 v[4:5], v110 offset0:2 offset1:3
	ds_read2st64_b32 v[6:7], v110 offset0:16 offset1:17
	ds_read2st64_b32 v[8:9], v110 offset0:18 offset1:19
	s_waitcnt lgkmcnt(0)
	v_cvt_pk_bf16_f32 v250, v2, v3
	v_cvt_pk_bf16_f32 v251, v4, v5
	v_cvt_pk_bf16_f32 v252, v6, v7
	v_cvt_pk_bf16_f32 v253, v8, v9
	s_nop 1
	v_mfma_f32_16x16x32_bf16 v[184:187], v[250:253], v[10:13], v[184:187]
	ds_read2st64_b32 v[2:3], v111 offset0:0 offset1:1
	ds_read2st64_b32 v[4:5], v111 offset0:2 offset1:3
	ds_read2st64_b32 v[6:7], v111 offset0:16 offset1:17
	ds_read2st64_b32 v[8:9], v111 offset0:18 offset1:19
	s_waitcnt lgkmcnt(0)
	v_cvt_pk_bf16_f32 v250, v2, v3
	v_cvt_pk_bf16_f32 v251, v4, v5
	v_cvt_pk_bf16_f32 v252, v6, v7
	v_cvt_pk_bf16_f32 v253, v8, v9
	s_nop 1
	v_mfma_f32_16x16x32_bf16 v[188:191], v[250:253], v[10:13], v[188:191]
	ds_read2st64_b32 v[2:3], v14 offset0:0 offset1:1
	ds_read2st64_b32 v[4:5], v14 offset0:2 offset1:3
	ds_read2st64_b32 v[6:7], v14 offset0:16 offset1:17
	ds_read2st64_b32 v[8:9], v14 offset0:18 offset1:19
	s_waitcnt lgkmcnt(0)
	v_cvt_pk_bf16_f32 v250, v2, v3
	v_cvt_pk_bf16_f32 v251, v4, v5
	v_cvt_pk_bf16_f32 v252, v6, v7
	v_cvt_pk_bf16_f32 v253, v8, v9
	s_nop 1
	v_mfma_f32_16x16x32_bf16 v[192:195], v[250:253], v[10:13], v[192:195]
	s_cmp_lg_u32 s72, 0
	s_cbranch_scc1 .Lsa_pv16_skip
	ds_write_b128 v105, v[232:235]
	ds_write_b128 v106, v[236:239] offset:1024
	ds_write_b128 v105, v[240:243] offset:2048
	ds_write_b128 v106, v[244:247] offset:3072
	v_cvt_pk_bf16_f32 v10, v176, v177
	v_cvt_pk_bf16_f32 v11, v178, v179
	v_mov_b32_e32 v12, 0
	v_mov_b32_e32 v13, 0
	ds_read2st64_b32 v[2:3], v109 offset0:0 offset1:1
	ds_read2st64_b32 v[4:5], v109 offset0:2 offset1:3
	s_waitcnt lgkmcnt(0)
	v_cvt_pk_bf16_f32 v250, v2, v3
	v_cvt_pk_bf16_f32 v251, v4, v5
	v_mov_b32_e32 v252, 0
	v_mov_b32_e32 v253, 0
	s_nop 1
	v_mfma_f32_16x16x32_bf16 v[180:183], v[250:253], v[10:13], v[180:183]
	ds_read2st64_b32 v[2:3], v110 offset0:0 offset1:1
	ds_read2st64_b32 v[4:5], v110 offset0:2 offset1:3
	s_waitcnt lgkmcnt(0)
	v_cvt_pk_bf16_f32 v250, v2, v3
	v_cvt_pk_bf16_f32 v251, v4, v5
	v_mov_b32_e32 v252, 0
	v_mov_b32_e32 v253, 0
	s_nop 1
	v_mfma_f32_16x16x32_bf16 v[184:187], v[250:253], v[10:13], v[184:187]
	ds_read2st64_b32 v[2:3], v111 offset0:0 offset1:1
	ds_read2st64_b32 v[4:5], v111 offset0:2 offset1:3
	s_waitcnt lgkmcnt(0)
	v_cvt_pk_bf16_f32 v250, v2, v3
	v_cvt_pk_bf16_f32 v251, v4, v5
	v_mov_b32_e32 v252, 0
	v_mov_b32_e32 v253, 0
	s_nop 1
	v_mfma_f32_16x16x32_bf16 v[188:191], v[250:253], v[10:13], v[188:191]
	ds_read2st64_b32 v[2:3], v14 offset0:0 offset1:1
	ds_read2st64_b32 v[4:5], v14 offset0:2 offset1:3
	s_waitcnt lgkmcnt(0)
	v_cvt_pk_bf16_f32 v250, v2, v3
	v_cvt_pk_bf16_f32 v251, v4, v5
	v_mov_b32_e32 v252, 0
	v_mov_b32_e32 v253, 0
	s_nop 1
	v_mfma_f32_16x16x32_bf16 v[192:195], v[250:253], v[10:13], v[192:195]

.LBB0_1905:
	v_add_u32_e32 v2, s4, v206
	ds_read_b64_tr_b16 v[182:183], v2 offset:24576
	ds_read_b64_tr_b16 v[184:185], v2 offset:25088
	s_waitcnt lgkmcnt(4)
	v_mfma_f32_32x32x16_bf16 v[66:81], v[174:177], v[126:129], v[66:81]
	v_add_f32_e32 v4, v98, v99
	v_add_f32_e32 v4, v100, v4
	v_add_f32_e32 v4, v101, v4
	v_add_f32_e32 v4, v102, v4
	v_add_f32_e32 v4, v103, v4
	v_cvt_pk_bf16_f32 v142, v98, v99
	v_cvt_pk_bf16_f32 v143, v100, v101
	ds_read_b64_tr_b16 v[178:179], v2 offset:28672
	ds_read_b64_tr_b16 v[180:181], v2 offset:29184
	s_waitcnt lgkmcnt(4)
	v_mfma_f32_32x32x16_bf16 v[50:65], v[170:173], v[126:129], v[50:65]
	v_add_f32_e32 v4, v104, v4
	v_add_f32_e32 v4, v105, v4
	v_add_f32_e32 v4, v106, v4
	v_add_f32_e32 v4, v107, v4
	v_cvt_pk_bf16_f32 v144, v102, v103
	v_cvt_pk_bf16_f32 v145, v104, v105
	ds_read_b64_tr_b16 v[12:13], v2 offset:25600
	ds_read_b64_tr_b16 v[14:15], v2 offset:26112
	v_mfma_f32_32x32x16_bf16 v[66:81], v[166:169], v[122:125], v[66:81]
	v_add_f32_e32 v4, v108, v4
	v_add_f32_e32 v4, v109, v4
	v_add_f32_e32 v4, v110, v4
	v_add_f32_e32 v4, v111, v4
	v_cvt_pk_bf16_f32 v138, v106, v107
	v_cvt_pk_bf16_f32 v139, v108, v109
	ds_read_b64_tr_b16 v[8:9], v2 offset:29696
	ds_read_b64_tr_b16 v[10:11], v2 offset:30208
	v_mfma_f32_32x32x16_bf16 v[50:65], v[162:165], v[122:125], v[50:65]
	v_add_f32_e32 v4, v112, v4
	v_add_f32_e32 v4, v113, v4
	v_add_f32_e32 v4, v82, v4
	v_add_f32_e32 v16, v83, v4
	v_cvt_pk_bf16_f32 v140, v110, v111
	v_cvt_pk_bf16_f32 v141, v112, v113
	ds_read_b64_tr_b16 v[4:5], v2 offset:26624
	ds_read_b64_tr_b16 v[6:7], v2 offset:27136
	v_mfma_f32_32x32x16_bf16 v[66:81], v[158:161], v[118:121], v[66:81]
	v_add_f32_e32 v16, v84, v16
	v_add_f32_e32 v16, v85, v16
	v_add_f32_e32 v16, v86, v16
	v_add_f32_e32 v16, v87, v16
	v_cvt_pk_bf16_f32 v134, v82, v83
	v_cvt_pk_bf16_f32 v135, v84, v85
	ds_read_b64_tr_b16 v[174:175], v2 offset:30720
	ds_read_b64_tr_b16 v[176:177], v2 offset:31232
	v_mfma_f32_32x32x16_bf16 v[50:65], v[154:157], v[118:121], v[50:65]
	v_add_f32_e32 v16, v88, v16
	v_add_f32_e32 v16, v89, v16
	v_add_f32_e32 v16, v90, v16
	v_add_f32_e32 v16, v91, v16
	v_cvt_pk_bf16_f32 v136, v86, v87
	v_cvt_pk_bf16_f32 v137, v88, v89
	ds_read_b64_tr_b16 v[170:171], v2 offset:27648
	ds_read_b64_tr_b16 v[172:173], v2 offset:28160
	v_mfma_f32_32x32x16_bf16 v[66:81], v[150:153], v[114:117], v[66:81]
	v_add_f32_e32 v16, v92, v16
	v_add_f32_e32 v16, v93, v16
	v_add_f32_e32 v16, v94, v16
	v_add_f32_e32 v16, v95, v16
	v_cvt_pk_bf16_f32 v130, v90, v91
	v_cvt_pk_bf16_f32 v131, v92, v93
	ds_read_b64_tr_b16 v[166:167], v2 offset:31744
	ds_read_b64_tr_b16 v[168:169], v2 offset:32256
	v_mfma_f32_32x32x16_bf16 v[50:65], v[146:149], v[114:117], v[50:65]
	v_add_f32_e32 v2, v96, v16
	v_add_f32_e32 v2, v97, v2
	v_add_f32_e32 v2, 0, v2
	v_cvt_pk_bf16_f32 v132, v94, v95
	v_cvt_pk_bf16_f32 v133, v96, v97
	s_nop 0
	v_add_f32_e32 v16, v211, v2
	v_max_f32_e32 v2, v67, v67
	v_max_f32_e32 v17, v66, v66
	v_max_f32_e32 v2, v17, v2
	s_nop 2
	v_max3_f32 v17, v68, v69, v51
	v_max3_f32 v2, v2, v50, v52
	v_max3_f32 v2, v2, v53, v70
	v_max3_f32 v17, v17, v72, v73
	v_max3_f32 v2, v2, v71, v54
	v_max3_f32 v17, v17, v56, v57
	v_max3_f32 v2, v2, v55, v74
	v_max3_f32 v17, v17, v76, v77
	v_max3_f32 v2, v2, v75, v58
	v_max3_f32 v17, v17, v60, v61
	v_max3_f32 v2, v2, v59, v78
	v_max3_f32 v17, v17, v80, v81
	v_max3_f32 v2, v2, v79, v62
	v_max3_f32 v17, v17, v64, v65
	v_max3_f32 v2, v2, v63, v17
	v_mov_b32_e32 v17, v2
	s_nop 1
	v_permlane32_swap_b32_e32 v2, v17
	v_max_f32_e32 v17, v17, v17
	v_max_f32_e32 v2, v2, v2
	v_max_f32_e32 v2, v2, v17
	v_lshl_add_u64 v[82:83], v[192:193], 0, s[18:19]
	s_add_i32 s4, s37, s77
	s_mov_b32 s5, m0
	s_mov_b32 m0, s4
	s_nop 0
	global_load_lds_dwordx4 v[82:83], off
	s_mov_b32 m0, s5
	v_sub_f32_e32 v2, v2, v208
	v_lshl_add_u64 v[82:83], v[190:191], 0, s[18:19]
	s_add_i32 s4, s35, s78
	s_mov_b32 s5, m0
	s_mov_b32 m0, s4
	s_nop 0
	global_load_lds_dwordx4 v[82:83], off
	s_mov_b32 m0, s5
	v_cmp_lt_f32_e32 vcc, s66, v2
	s_cmp_lg_u64 vcc, 0
	s_cselect_b64 s[6:7], -1, 0
	s_cbranch_vccz .LBB0_1909
	v_max_f32_e32 v2, v2, v2
	v_max_f32_e32 v17, 0, v2
	v_exp_f32_e64 v2, -v17
	s_and_saveexec_b64 s[4:5], s[0:1]
	ds_write_b32 v207, v2 offset:49152
	s_or_b64 exec, exec, s[4:5]
	v_add_f32_e32 v208, v208, v17
	v_mul_f32_e32 v16, v16, v2

.LBB0_1911:
	s_add_i32 s4, s35, 0x2000
	s_cmpk_lg_i32 s35, 0x4000
	s_cselect_b32 s80, s4, 0
	v_add_u32_e32 v17, s37, v206
	ds_read_b64_tr_b16 v[170:171], v17 offset:24576
	ds_read_b64_tr_b16 v[172:173], v17 offset:25088
	s_waitcnt lgkmcnt(9)
	v_mfma_f32_32x32x16_bf16 v[98:113], v[162:165], v[126:129], v[98:113]
	v_add_f32_e32 v130, v66, v67
	v_add_f32_e32 v130, v68, v130
	v_add_f32_e32 v130, v69, v130
	v_add_f32_e32 v130, v70, v130
	v_add_f32_e32 v130, v71, v130
	v_cvt_pk_bf16_f32 v142, v66, v67
	v_cvt_pk_bf16_f32 v143, v68, v69
	ds_read_b64_tr_b16 v[166:167], v17 offset:28672
	ds_read_b64_tr_b16 v[168:169], v17 offset:29184
	s_waitcnt lgkmcnt(10)
	v_mfma_f32_32x32x16_bf16 v[82:97], v[154:157], v[126:129], v[82:97]
	v_add_f32_e32 v66, v72, v130
	v_add_f32_e32 v66, v73, v66
	v_add_f32_e32 v66, v74, v66
	v_add_f32_e32 v66, v75, v66
	v_cvt_pk_bf16_f32 v144, v70, v71
	v_cvt_pk_bf16_f32 v145, v72, v73
	ds_read_b64_tr_b16 v[162:163], v17 offset:25600
	ds_read_b64_tr_b16 v[164:165], v17 offset:26112
	s_waitcnt lgkmcnt(11)
	v_mfma_f32_32x32x16_bf16 v[98:113], v[158:161], v[122:125], v[98:113]
	v_add_f32_e32 v66, v76, v66
	v_add_f32_e32 v66, v77, v66
	v_add_f32_e32 v66, v78, v66
	v_add_f32_e32 v66, v79, v66
	v_cvt_pk_bf16_f32 v138, v74, v75
	v_cvt_pk_bf16_f32 v139, v76, v77
	ds_read_b64_tr_b16 v[154:155], v17 offset:29696
	ds_read_b64_tr_b16 v[156:157], v17 offset:30208
	s_waitcnt lgkmcnt(12)
	v_mfma_f32_32x32x16_bf16 v[82:97], v[146:149], v[122:125], v[82:97]
	v_add_f32_e32 v66, v80, v66
	v_add_f32_e32 v66, v81, v66
	v_add_f32_e32 v66, v50, v66
	v_add_f32_e32 v66, v51, v66
	v_cvt_pk_bf16_f32 v140, v78, v79
	v_cvt_pk_bf16_f32 v141, v80, v81
	ds_read_b64_tr_b16 v[146:147], v17 offset:26624
	ds_read_b64_tr_b16 v[148:149], v17 offset:27136
	s_waitcnt lgkmcnt(13)
	v_mfma_f32_32x32x16_bf16 v[98:113], v[150:153], v[118:121], v[98:113]
	v_add_f32_e32 v66, v52, v66
	v_add_f32_e32 v66, v53, v66
	v_add_f32_e32 v66, v54, v66
	v_add_f32_e32 v66, v55, v66
	v_cvt_pk_bf16_f32 v134, v50, v51
	v_cvt_pk_bf16_f32 v135, v52, v53
	ds_read_b64_tr_b16 v[182:183], v17 offset:30720
	ds_read_b64_tr_b16 v[184:185], v17 offset:31232
	s_waitcnt lgkmcnt(14)
	v_mfma_f32_32x32x16_bf16 v[82:97], v[8:11], v[118:121], v[82:97]
	v_add_f32_e32 v50, v56, v66
	v_add_f32_e32 v50, v57, v50
	v_add_f32_e32 v50, v58, v50
	v_add_f32_e32 v50, v59, v50
	v_cvt_pk_bf16_f32 v136, v54, v55
	v_cvt_pk_bf16_f32 v137, v56, v57
	ds_read_b64_tr_b16 v[178:179], v17 offset:27648
	ds_read_b64_tr_b16 v[180:181], v17 offset:28160
	s_waitcnt lgkmcnt(14)
	v_mfma_f32_32x32x16_bf16 v[98:113], v[12:15], v[114:117], v[98:113]
	v_add_f32_e32 v8, v60, v50
	v_add_f32_e32 v8, v61, v8
	v_add_f32_e32 v8, v62, v8
	v_add_f32_e32 v50, v63, v8
	v_cvt_pk_bf16_f32 v130, v58, v59
	v_cvt_pk_bf16_f32 v131, v60, v61
	ds_read_b64_tr_b16 v[8:9], v17 offset:31744
	ds_read_b64_tr_b16 v[10:11], v17 offset:32256
	v_mfma_f32_32x32x16_bf16 v[82:97], v[4:7], v[114:117], v[82:97]
	v_add_f32_e32 v12, v64, v50
	v_add_f32_e32 v12, v65, v12
	v_add_f32_e32 v12, 0, v12
	v_cvt_pk_bf16_f32 v132, v62, v63
	v_cvt_pk_bf16_f32 v133, v64, v65
	v_max_f32_e32 v4, v99, v99
	v_max_f32_e32 v5, v98, v98
	v_max_f32_e32 v4, v5, v4
	s_nop 4
	v_max3_f32 v5, v100, v101, v83
	v_max3_f32 v4, v4, v82, v84
	v_max3_f32 v4, v4, v85, v102
	v_max3_f32 v5, v5, v104, v105
	v_max3_f32 v4, v4, v103, v86
	v_max3_f32 v5, v5, v88, v89
	v_max3_f32 v4, v4, v87, v106
	v_max3_f32 v5, v5, v108, v109
	v_max3_f32 v4, v4, v107, v90
	v_max3_f32 v5, v5, v92, v93
	v_max3_f32 v4, v4, v91, v110
	v_max3_f32 v5, v5, v112, v113
	v_max3_f32 v4, v4, v111, v94
	v_max3_f32 v5, v5, v96, v97
	v_max3_f32 v4, v4, v95, v5
	v_mov_b32_e32 v5, v4
	s_nop 1
	v_permlane32_swap_b32_e32 v4, v5
	v_max_f32_e32 v5, v5, v5
	v_max_f32_e32 v4, v4, v4
	v_max_f32_e32 v4, v4, v5
	s_add_i32 s4, s35, s77
	s_mov_b32 s5, m0
	s_mov_b32 m0, s4
	s_nop 0
	global_load_lds_dwordx4 v[192:193], off
	s_mov_b32 m0, s5
	v_sub_f32_e32 v4, v4, v208
	s_add_i32 s4, s80, s78
	s_mov_b32 s5, m0
	s_mov_b32 m0, s4
	s_nop 0
	global_load_lds_dwordx4 v[190:191], off
	s_mov_b32 m0, s5
	v_cmp_lt_f32_e32 vcc, s66, v4
	s_cmp_lg_u64 vcc, 0
	v_add_f32_e32 v211, v16, v12
	s_cselect_b64 s[6:7], -1, 0
	s_cbranch_vccz .LBB0_1915
	v_max_f32_e32 v4, v4, v4
	v_max_f32_e32 v5, 0, v4
	v_exp_f32_e64 v4, -v5
	s_and_saveexec_b64 s[4:5], s[0:1]
	ds_write_b32 v207, v4 offset:49152
	s_or_b64 exec, exec, s[4:5]
	v_add_f32_e32 v208, v208, v5
	v_mul_f32_e32 v211, v211, v4

.LBB0_1924:
	v_add_u32_e32 v6, s35, v206
	ds_read_b64_tr_b16 v[190:191], v6 offset:24576
	ds_read_b64_tr_b16 v[192:193], v6 offset:25088
	s_waitcnt lgkmcnt(4)
	v_mfma_f32_32x32x16_bf16 v[66:81], v[174:177], v[126:129], v[66:81]
	v_add_f32_e32 v4, v98, v99
	v_add_f32_e32 v4, v100, v4
	v_add_f32_e32 v4, v101, v4
	v_add_f32_e32 v4, v102, v4
	v_add_f32_e32 v4, v103, v4
	v_cvt_pk_bf16_f32 v142, v98, v99
	v_cvt_pk_bf16_f32 v143, v100, v101
	ds_read_b64_tr_b16 v[174:175], v6 offset:28672
	ds_read_b64_tr_b16 v[176:177], v6 offset:29184
	s_waitcnt lgkmcnt(4)
	v_mfma_f32_32x32x16_bf16 v[50:65], v[170:173], v[126:129], v[50:65]
	v_add_f32_e32 v4, v104, v4
	v_add_f32_e32 v4, v105, v4
	v_add_f32_e32 v4, v106, v4
	v_add_f32_e32 v4, v107, v4
	v_cvt_pk_bf16_f32 v144, v102, v103
	v_cvt_pk_bf16_f32 v145, v104, v105
	ds_read_b64_tr_b16 v[186:187], v6 offset:25600
	ds_read_b64_tr_b16 v[188:189], v6 offset:26112
	v_mfma_f32_32x32x16_bf16 v[66:81], v[166:169], v[122:125], v[66:81]
	v_add_f32_e32 v4, v108, v4
	v_add_f32_e32 v4, v109, v4
	v_add_f32_e32 v4, v110, v4
	v_add_f32_e32 v4, v111, v4
	v_cvt_pk_bf16_f32 v138, v106, v107
	v_cvt_pk_bf16_f32 v139, v108, v109
	ds_read_b64_tr_b16 v[182:183], v6 offset:29696
	ds_read_b64_tr_b16 v[184:185], v6 offset:30208
	v_mfma_f32_32x32x16_bf16 v[50:65], v[162:165], v[122:125], v[50:65]
	v_add_f32_e32 v4, v112, v4
	v_add_f32_e32 v4, v113, v4
	v_add_f32_e32 v4, v82, v4
	v_add_f32_e32 v4, v83, v4
	v_cvt_pk_bf16_f32 v140, v110, v111
	v_cvt_pk_bf16_f32 v141, v112, v113
	ds_read_b64_tr_b16 v[178:179], v6 offset:26624
	ds_read_b64_tr_b16 v[180:181], v6 offset:27136
	v_mfma_f32_32x32x16_bf16 v[66:81], v[158:161], v[118:121], v[66:81]
	v_add_f32_e32 v4, v84, v4
	v_add_f32_e32 v4, v85, v4
	v_add_f32_e32 v4, v86, v4
	v_add_f32_e32 v4, v87, v4
	v_cvt_pk_bf16_f32 v134, v82, v83
	v_cvt_pk_bf16_f32 v135, v84, v85
	ds_read_b64_tr_b16 v[12:13], v6 offset:30720
	ds_read_b64_tr_b16 v[14:15], v6 offset:31232
	v_mfma_f32_32x32x16_bf16 v[50:65], v[154:157], v[118:121], v[50:65]
	v_add_f32_e32 v4, v88, v4
	v_add_f32_e32 v4, v89, v4
	v_add_f32_e32 v4, v90, v4
	v_add_f32_e32 v4, v91, v4
	v_cvt_pk_bf16_f32 v136, v86, v87
	v_cvt_pk_bf16_f32 v137, v88, v89
	ds_read_b64_tr_b16 v[8:9], v6 offset:27648
	ds_read_b64_tr_b16 v[10:11], v6 offset:28160
	v_mfma_f32_32x32x16_bf16 v[66:81], v[150:153], v[114:117], v[66:81]
	v_add_f32_e32 v4, v92, v4
	v_add_f32_e32 v4, v93, v4
	v_add_f32_e32 v4, v94, v4
	v_add_f32_e32 v82, v95, v4
	v_cvt_pk_bf16_f32 v130, v90, v91
	v_cvt_pk_bf16_f32 v131, v92, v93
	ds_read_b64_tr_b16 v[4:5], v6 offset:31744
	ds_read_b64_tr_b16 v[6:7], v6 offset:32256
	v_mfma_f32_32x32x16_bf16 v[50:65], v[146:149], v[114:117], v[50:65]
	v_add_f32_e32 v82, v96, v82
	v_add_f32_e32 v82, v97, v82
	v_add_f32_e32 v82, 0, v82
	v_cvt_pk_bf16_f32 v132, v94, v95
	v_cvt_pk_bf16_f32 v133, v96, v97
	s_add_i32 s4, s8, 1
	s_cmp_ge_i32 s4, s79
	s_cselect_b64 s[34:35], -1, 0
	s_and_b64 vcc, exec, s[34:35]
	s_cbranch_vccnz .LBB0_1926
	s_add_i32 s4, s80, s77
	v_lshl_add_u64 v[84:85], v[200:201], 0, s[18:19]
	s_mov_b32 s5, m0
	s_mov_b32 m0, s4
	s_nop 0
	global_load_lds_dwordx4 v[84:85], off
	s_mov_b32 m0, s5

.LBB0_1938:
	v_add_u32_e32 v6, s80, v206
	ds_read_b64_tr_b16 v[194:195], v6 offset:24576
	ds_read_b64_tr_b16 v[196:197], v6 offset:25088
	s_waitcnt lgkmcnt(9)
	v_mfma_f32_32x32x16_bf16 v[98:113], v[174:177], v[126:129], v[98:113]
	v_add_f32_e32 v4, v66, v67
	v_add_f32_e32 v4, v68, v4
	v_add_f32_e32 v4, v69, v4
	v_add_f32_e32 v4, v70, v4
	v_add_f32_e32 v4, v71, v4
	v_cvt_pk_bf16_f32 v142, v66, v67
	v_cvt_pk_bf16_f32 v143, v68, v69
	ds_read_b64_tr_b16 v[190:191], v6 offset:28672
	ds_read_b64_tr_b16 v[192:193], v6 offset:29184
	s_waitcnt lgkmcnt(10)
	v_mfma_f32_32x32x16_bf16 v[82:97], v[170:173], v[126:129], v[82:97]
	v_add_f32_e32 v4, v72, v4
	v_add_f32_e32 v4, v73, v4
	v_add_f32_e32 v4, v74, v4
	v_add_f32_e32 v4, v75, v4
	v_cvt_pk_bf16_f32 v144, v70, v71
	v_cvt_pk_bf16_f32 v145, v72, v73
	ds_read_b64_tr_b16 v[186:187], v6 offset:25600
	ds_read_b64_tr_b16 v[188:189], v6 offset:26112
	s_waitcnt lgkmcnt(11)
	v_mfma_f32_32x32x16_bf16 v[98:113], v[166:169], v[122:125], v[98:113]
	v_add_f32_e32 v4, v76, v4
	v_add_f32_e32 v4, v77, v4
	v_add_f32_e32 v4, v78, v4
	v_add_f32_e32 v4, v79, v4
	v_cvt_pk_bf16_f32 v138, v74, v75
	v_cvt_pk_bf16_f32 v139, v76, v77
	ds_read_b64_tr_b16 v[182:183], v6 offset:29696
	ds_read_b64_tr_b16 v[184:185], v6 offset:30208
	s_waitcnt lgkmcnt(12)
	v_mfma_f32_32x32x16_bf16 v[82:97], v[162:165], v[122:125], v[82:97]
	v_add_f32_e32 v4, v80, v4
	v_add_f32_e32 v4, v81, v4
	v_add_f32_e32 v4, v50, v4
	v_add_f32_e32 v4, v51, v4
	v_cvt_pk_bf16_f32 v140, v78, v79
	v_cvt_pk_bf16_f32 v141, v80, v81
	ds_read_b64_tr_b16 v[178:179], v6 offset:26624
	ds_read_b64_tr_b16 v[180:181], v6 offset:27136
	s_waitcnt lgkmcnt(13)
	v_mfma_f32_32x32x16_bf16 v[98:113], v[158:161], v[118:121], v[98:113]
	v_add_f32_e32 v4, v52, v4
	v_add_f32_e32 v4, v53, v4
	v_add_f32_e32 v4, v54, v4
	v_add_f32_e32 v4, v55, v4
	v_cvt_pk_bf16_f32 v134, v50, v51
	v_cvt_pk_bf16_f32 v135, v52, v53
	ds_read_b64_tr_b16 v[12:13], v6 offset:30720
	ds_read_b64_tr_b16 v[14:15], v6 offset:31232
	s_waitcnt lgkmcnt(14)
	v_mfma_f32_32x32x16_bf16 v[82:97], v[154:157], v[118:121], v[82:97]
	v_add_f32_e32 v4, v56, v4
	v_add_f32_e32 v4, v57, v4
	v_add_f32_e32 v4, v58, v4
	v_add_f32_e32 v4, v59, v4
	v_cvt_pk_bf16_f32 v136, v54, v55
	v_cvt_pk_bf16_f32 v137, v56, v57
	ds_read_b64_tr_b16 v[8:9], v6 offset:27648
	ds_read_b64_tr_b16 v[10:11], v6 offset:28160
	s_waitcnt lgkmcnt(14)
	v_mfma_f32_32x32x16_bf16 v[98:113], v[150:153], v[114:117], v[98:113]
	v_add_f32_e32 v4, v60, v4
	v_add_f32_e32 v4, v61, v4
	v_add_f32_e32 v4, v62, v4
	v_add_f32_e32 v214, v63, v4
	v_cvt_pk_bf16_f32 v130, v58, v59
	v_cvt_pk_bf16_f32 v131, v60, v61
	ds_read_b64_tr_b16 v[4:5], v6 offset:31744
	ds_read_b64_tr_b16 v[6:7], v6 offset:32256
	v_mfma_f32_32x32x16_bf16 v[82:97], v[146:149], v[114:117], v[82:97]
	v_add_f32_e32 v132, v64, v214
	v_add_f32_e32 v132, v65, v132
	v_add_f32_e32 v214, 0, v132
	v_cvt_pk_bf16_f32 v132, v62, v63
	v_cvt_pk_bf16_f32 v133, v64, v65
	s_add_i32 s92, s8, 2
	s_cmp_ge_i32 s92, s79
	s_cselect_b64 s[36:37], -1, 0
	s_and_b64 vcc, exec, s[36:37]
	s_cbranch_vccnz .LBB0_1940
	s_add_i32 s4, s84, s77
	s_mov_b32 s5, m0
	s_mov_b32 m0, s4
	s_nop 0
	global_load_lds_dwordx4 v[200:201], off
	s_mov_b32 m0, s5

.LBB0_1971:
	v_add_u32_e32 v2, s84, v206
	ds_read_b64_tr_b16 v[178:179], v2 offset:24576
	ds_read_b64_tr_b16 v[180:181], v2 offset:25088
	s_waitcnt lgkmcnt(4)
	v_mfma_f32_32x32x16_bf16 v[66:81], v[174:177], v[126:129], v[66:81]
	v_add_f32_e32 v4, v98, v99
	v_add_f32_e32 v4, v100, v4
	v_add_f32_e32 v4, v101, v4
	v_add_f32_e32 v4, v102, v4
	v_add_f32_e32 v4, v103, v4
	v_cvt_pk_bf16_f32 v142, v98, v99
	v_cvt_pk_bf16_f32 v143, v100, v101
	ds_read_b64_tr_b16 v[174:175], v2 offset:28672
	ds_read_b64_tr_b16 v[176:177], v2 offset:29184
	s_waitcnt lgkmcnt(4)
	v_mfma_f32_32x32x16_bf16 v[50:65], v[170:173], v[126:129], v[50:65]
	v_add_f32_e32 v4, v104, v4
	v_add_f32_e32 v4, v105, v4
	v_add_f32_e32 v4, v106, v4
	v_add_f32_e32 v4, v107, v4
	v_cvt_pk_bf16_f32 v144, v102, v103
	v_cvt_pk_bf16_f32 v145, v104, v105
	ds_read_b64_tr_b16 v[126:127], v2 offset:25600
	ds_read_b64_tr_b16 v[128:129], v2 offset:26112
	v_mfma_f32_32x32x16_bf16 v[66:81], v[166:169], v[122:125], v[66:81]
	v_add_f32_e32 v4, v108, v4
	v_add_f32_e32 v4, v109, v4
	v_add_f32_e32 v4, v110, v4
	v_add_f32_e32 v4, v111, v4
	v_cvt_pk_bf16_f32 v138, v106, v107
	v_cvt_pk_bf16_f32 v139, v108, v109
	ds_read_b64_tr_b16 v[102:103], v2 offset:29696
	ds_read_b64_tr_b16 v[104:105], v2 offset:30208
	v_mfma_f32_32x32x16_bf16 v[50:65], v[162:165], v[122:125], v[50:65]
	v_add_f32_e32 v4, v112, v4
	v_add_f32_e32 v4, v113, v4
	v_add_f32_e32 v4, v82, v4
	v_add_f32_e32 v4, v83, v4
	v_cvt_pk_bf16_f32 v140, v110, v111
	v_cvt_pk_bf16_f32 v141, v112, v113
	ds_read_b64_tr_b16 v[98:99], v2 offset:26624
	ds_read_b64_tr_b16 v[100:101], v2 offset:27136
	v_mfma_f32_32x32x16_bf16 v[66:81], v[158:161], v[118:121], v[66:81]
	v_add_f32_e32 v4, v84, v4
	v_add_f32_e32 v4, v85, v4
	v_add_f32_e32 v4, v86, v4
	v_add_f32_e32 v4, v87, v4
	v_cvt_pk_bf16_f32 v134, v82, v83
	v_cvt_pk_bf16_f32 v135, v84, v85
	ds_read_b64_tr_b16 v[12:13], v2 offset:30720
	ds_read_b64_tr_b16 v[14:15], v2 offset:31232
	v_mfma_f32_32x32x16_bf16 v[50:65], v[154:157], v[118:121], v[50:65]
	v_add_f32_e32 v4, v88, v4
	v_add_f32_e32 v4, v89, v4
	v_add_f32_e32 v4, v90, v4
	v_add_f32_e32 v4, v91, v4
	v_cvt_pk_bf16_f32 v136, v86, v87
	v_cvt_pk_bf16_f32 v137, v88, v89
	ds_read_b64_tr_b16 v[8:9], v2 offset:27648
	ds_read_b64_tr_b16 v[10:11], v2 offset:28160
	v_mfma_f32_32x32x16_bf16 v[66:81], v[150:153], v[114:117], v[66:81]
	v_add_f32_e32 v4, v92, v4
	v_add_f32_e32 v4, v93, v4
	v_add_f32_e32 v4, v94, v4
	v_add_f32_e32 v16, v95, v4
	v_cvt_pk_bf16_f32 v130, v90, v91
	v_cvt_pk_bf16_f32 v131, v92, v93
	ds_read_b64_tr_b16 v[4:5], v2 offset:31744
	ds_read_b64_tr_b16 v[6:7], v2 offset:32256
	v_mfma_f32_32x32x16_bf16 v[50:65], v[146:149], v[114:117], v[50:65]
	v_add_f32_e32 v2, v96, v16
	v_add_f32_e32 v2, v97, v2
	v_add_f32_e32 v2, 0, v2
	v_cvt_pk_bf16_f32 v132, v94, v95
	v_cvt_pk_bf16_f32 v133, v96, v97
	v_or_b32_e32 v16, 0xe0, v205
	v_or_b32_e32 v17, 0xc0, v205
	v_cmp_le_i32_e32 vcc, v16, v209
	v_add_f32_e32 v2, v211, v2
	s_nop 3
	v_cndmask_b32_e32 v16, v199, v50, vcc
	v_cmp_lt_i32_e32 vcc, v17, v209
	s_nop 1
	v_cndmask_b32_e32 v50, v199, v67, vcc
	v_cmp_le_i32_e32 vcc, v17, v209
	v_or_b32_e32 v17, 0xe1, v205
	v_or_b32_e32 v67, 0xe2, v205
	v_cndmask_b32_e32 v66, v199, v66, vcc
	v_cmp_le_i32_e32 vcc, v17, v209
	s_nop 1
	v_cndmask_b32_e32 v17, v199, v51, vcc
	v_or_b32_e32 v51, 0xc2, v205
	v_cmp_le_i32_e32 vcc, v51, v209
	s_nop 1
	v_cndmask_b32_e32 v51, v199, v68, vcc
	v_cmp_le_i32_e32 vcc, v67, v209
	v_or_b32_e32 v67, 0xc3, v205
	v_max_f32_e32 v68, v66, v66
	v_cndmask_b32_e32 v52, v199, v52, vcc
	v_cmp_le_i32_e32 vcc, v67, v209
	v_or_b32_e32 v67, 0xe3, v205
	s_nop 0
	v_cndmask_b32_e32 v69, v199, v69, vcc
	v_cmp_le_i32_e32 vcc, v67, v209
	v_or_b32_e32 v67, 0xc8, v205
	s_nop 0
	v_cndmask_b32_e32 v53, v199, v53, vcc
	v_cmp_le_i32_e32 vcc, v67, v209
	v_or_b32_e32 v67, 0xe8, v205
	s_nop 0
	v_cndmask_b32_e32 v70, v199, v70, vcc
	v_cmp_le_i32_e32 vcc, v67, v209
	v_or_b32_e32 v67, 0xc9, v205
	s_nop 0
	v_cndmask_b32_e32 v54, v199, v54, vcc
	v_cmp_le_i32_e32 vcc, v67, v209
	v_or_b32_e32 v67, 0xe9, v205
	s_nop 0
	v_cndmask_b32_e32 v71, v199, v71, vcc
	v_cmp_le_i32_e32 vcc, v67, v209
	v_or_b32_e32 v67, 0xca, v205
	s_nop 0
	v_cndmask_b32_e32 v55, v199, v55, vcc
	v_cmp_le_i32_e32 vcc, v67, v209
	v_or_b32_e32 v67, 0xea, v205
	s_nop 0
	v_cndmask_b32_e32 v72, v199, v72, vcc
	v_cmp_le_i32_e32 vcc, v67, v209
	v_or_b32_e32 v67, 0xcb, v205
	s_nop 0
	v_cndmask_b32_e32 v56, v199, v56, vcc
	v_cmp_le_i32_e32 vcc, v67, v209
	v_or_b32_e32 v67, 0xeb, v205
	s_nop 0
	v_cndmask_b32_e32 v73, v199, v73, vcc
	v_cmp_le_i32_e32 vcc, v67, v209
	v_or_b32_e32 v67, 0xd0, v205
	s_nop 0
	v_cndmask_b32_e32 v57, v199, v57, vcc
	v_cmp_le_i32_e32 vcc, v67, v209
	v_or_b32_e32 v67, 0xf0, v205
	s_nop 0
	v_cndmask_b32_e32 v74, v199, v74, vcc
	v_cmp_le_i32_e32 vcc, v67, v209
	v_or_b32_e32 v67, 0xd1, v205
	s_nop 0
	v_cndmask_b32_e32 v58, v199, v58, vcc
	v_cmp_le_i32_e32 vcc, v67, v209
	v_or_b32_e32 v67, 0xf1, v205
	s_nop 0
	v_cndmask_b32_e32 v75, v199, v75, vcc
	v_cmp_le_i32_e32 vcc, v67, v209
	v_or_b32_e32 v67, 0xd2, v205
	s_nop 0
	v_cndmask_b32_e32 v59, v199, v59, vcc
	v_cmp_le_i32_e32 vcc, v67, v209
	v_or_b32_e32 v67, 0xf2, v205
	s_nop 0
	v_cndmask_b32_e32 v76, v199, v76, vcc
	v_cmp_le_i32_e32 vcc, v67, v209
	v_or_b32_e32 v67, 0xd3, v205
	s_nop 0
	v_cndmask_b32_e32 v60, v199, v60, vcc
	v_cmp_le_i32_e32 vcc, v67, v209
	v_or_b32_e32 v67, 0xf3, v205
	s_nop 0
	v_cndmask_b32_e32 v77, v199, v77, vcc
	v_cmp_le_i32_e32 vcc, v67, v209
	v_or_b32_e32 v67, 0xd8, v205
	s_nop 0
	v_cndmask_b32_e32 v61, v199, v61, vcc
	v_cmp_le_i32_e32 vcc, v67, v209
	v_or_b32_e32 v67, 0xf8, v205
	s_nop 0
	v_cndmask_b32_e32 v78, v199, v78, vcc
	v_cmp_le_i32_e32 vcc, v67, v209
	v_or_b32_e32 v67, 0xd9, v205
	s_nop 0
	v_cndmask_b32_e32 v62, v199, v62, vcc
	v_cmp_le_i32_e32 vcc, v67, v209
	v_or_b32_e32 v67, 0xf9, v205
	s_nop 0
	v_cndmask_b32_e32 v79, v199, v79, vcc
	v_cmp_le_i32_e32 vcc, v67, v209
	v_or_b32_e32 v67, 0xda, v205
	s_nop 0
	v_cndmask_b32_e32 v63, v199, v63, vcc
	v_cmp_le_i32_e32 vcc, v67, v209
	v_or_b32_e32 v67, 0xfa, v205
	s_nop 0
	v_cndmask_b32_e32 v80, v199, v80, vcc
	v_cmp_le_i32_e32 vcc, v67, v209
	v_or_b32_e32 v67, 0xdb, v205
	s_nop 0
	v_cndmask_b32_e32 v64, v199, v64, vcc
	v_cmp_le_i32_e32 vcc, v67, v209
	v_or_b32_e32 v67, 0xfb, v205
	s_nop 0
	v_cndmask_b32_e32 v81, v199, v81, vcc
	v_cmp_le_i32_e32 vcc, v67, v209
	v_max_f32_e32 v67, v50, v50
	v_max_f32_e32 v67, v68, v67
	v_max3_f32 v68, v51, v69, v17
	v_max3_f32 v67, v67, v16, v52
	v_max3_f32 v67, v67, v53, v70
	v_max3_f32 v68, v68, v72, v73
	v_max3_f32 v67, v67, v71, v54
	v_max3_f32 v68, v68, v56, v57
	v_max3_f32 v67, v67, v55, v74
	v_max3_f32 v68, v68, v76, v77
	v_max3_f32 v67, v67, v75, v58
	v_max3_f32 v68, v68, v60, v61
	v_cndmask_b32_e32 v65, v199, v65, vcc
	v_max3_f32 v67, v67, v59, v78
	v_max3_f32 v68, v68, v80, v81
	v_max3_f32 v67, v67, v79, v62
	v_max3_f32 v68, v68, v64, v65
	v_max3_f32 v67, v67, v63, v68
	v_mov_b32_e32 v68, v67
	s_nop 1
	v_permlane32_swap_b32_e32 v67, v68
	v_max_f32_e32 v68, v68, v68
	v_max_f32_e32 v67, v67, v67
	v_max_f32_e32 v67, v67, v68
	v_sub_f32_e32 v67, v67, v208
	v_cmp_lt_f32_e32 vcc, s66, v67
	s_cmp_lg_u64 vcc, 0
	s_cselect_b64 s[0:1], -1, 0
	s_cbranch_vccz .LBB0_1975
	v_max_f32_e32 v67, v67, v67
	v_max_f32_e32 v68, 0, v67
	v_exp_f32_e64 v67, -v68
	v_cmp_gt_u32_e32 vcc, 32, v202
	s_and_saveexec_b64 s[4:5], vcc
	ds_write_b32 v207, v67 offset:49152
	s_or_b64 exec, exec, s[4:5]
	v_add_f32_e32 v208, v208, v68
	v_mul_f32_e32 v2, v2, v67

.LBB0_1980:
	v_add_u32_e32 v2, s4, v209
	ds_read_b64_tr_b16 v[184:185], v2 offset:24576
	ds_read_b64_tr_b16 v[186:187], v2 offset:25088
	s_waitcnt lgkmcnt(2)
	v_mfma_f32_32x32x16_bf16 v[52:67], v[160:163], v[128:131], v[52:67]
	v_add_f32_e32 v100, v84, v85
	v_add_f32_e32 v100, v86, v100
	v_add_f32_e32 v100, v87, v100
	v_add_f32_e32 v100, v88, v100
	v_add_f32_e32 v100, v89, v100
	v_cvt_pk_bf16_f32 v120, v84, v85
	v_cvt_pk_bf16_f32 v121, v86, v87
	ds_read_b64_tr_b16 v[160:161], v2 offset:28672
	ds_read_b64_tr_b16 v[162:163], v2 offset:29184
	v_mfma_f32_32x32x16_bf16 v[36:51], v[156:159], v[128:131], v[36:51]
	v_add_f32_e32 v84, v90, v100
	v_add_f32_e32 v84, v91, v84
	v_add_f32_e32 v84, v92, v84
	v_add_f32_e32 v84, v93, v84
	v_cvt_pk_bf16_f32 v122, v88, v89
	v_cvt_pk_bf16_f32 v123, v90, v91
	ds_read_b64_tr_b16 v[156:157], v2 offset:25600
	ds_read_b64_tr_b16 v[158:159], v2 offset:26112
	v_mfma_f32_32x32x16_bf16 v[52:67], v[152:155], v[124:127], v[52:67]
	v_add_f32_e32 v84, v94, v84
	v_add_f32_e32 v84, v95, v84
	v_add_f32_e32 v84, v96, v84
	v_add_f32_e32 v84, v97, v84
	v_cvt_pk_bf16_f32 v112, v92, v93
	v_cvt_pk_bf16_f32 v113, v94, v95
	ds_read_b64_tr_b16 v[180:181], v2 offset:29696
	ds_read_b64_tr_b16 v[182:183], v2 offset:30208
	v_mfma_f32_32x32x16_bf16 v[36:51], v[148:151], v[124:127], v[36:51]
	v_add_f32_e32 v84, v98, v84
	v_add_f32_e32 v84, v99, v84
	v_add_f32_e32 v84, v68, v84
	v_add_f32_e32 v84, v69, v84
	v_cvt_pk_bf16_f32 v114, v96, v97
	v_cvt_pk_bf16_f32 v115, v98, v99
	ds_read_b64_tr_b16 v[176:177], v2 offset:26624
	ds_read_b64_tr_b16 v[178:179], v2 offset:27136
	v_mfma_f32_32x32x16_bf16 v[52:67], v[144:147], v[116:119], v[52:67]
	v_add_f32_e32 v84, v70, v84
	v_add_f32_e32 v84, v71, v84
	v_add_f32_e32 v84, v72, v84
	v_add_f32_e32 v84, v73, v84
	v_cvt_pk_bf16_f32 v104, v68, v69
	v_cvt_pk_bf16_f32 v105, v70, v71
	ds_read_b64_tr_b16 v[172:173], v2 offset:30720
	ds_read_b64_tr_b16 v[174:175], v2 offset:31232
	v_mfma_f32_32x32x16_bf16 v[36:51], v[140:143], v[116:119], v[36:51]
	v_add_f32_e32 v68, v74, v84
	v_add_f32_e32 v68, v75, v68
	v_add_f32_e32 v68, v76, v68
	v_add_f32_e32 v68, v77, v68
	v_cvt_pk_bf16_f32 v106, v72, v73
	v_cvt_pk_bf16_f32 v107, v74, v75
	ds_read_b64_tr_b16 v[168:169], v2 offset:27648
	ds_read_b64_tr_b16 v[170:171], v2 offset:28160
	v_mfma_f32_32x32x16_bf16 v[52:67], v[136:139], v[108:111], v[52:67]
	v_add_f32_e32 v68, v78, v68
	v_add_f32_e32 v68, v79, v68
	v_add_f32_e32 v68, v80, v68
	v_add_f32_e32 v68, v81, v68
	v_cvt_pk_bf16_f32 v100, v76, v77
	v_cvt_pk_bf16_f32 v101, v78, v79
	ds_read_b64_tr_b16 v[164:165], v2 offset:31744
	ds_read_b64_tr_b16 v[166:167], v2 offset:32256
	v_mfma_f32_32x32x16_bf16 v[36:51], v[132:135], v[108:111], v[36:51]
	v_add_f32_e32 v2, v82, v68
	v_add_f32_e32 v2, v83, v2
	v_add_f32_e32 v2, 0, v2
	v_cvt_pk_bf16_f32 v102, v80, v81
	v_cvt_pk_bf16_f32 v103, v82, v83
	v_lshl_add_u64 v[68:69], v[190:191], 0, s[18:19]
	s_add_i32 s4, s27, s37
	s_mov_b32 s5, m0
	s_mov_b32 m0, s4
	s_nop 0
	global_load_lds_dwordx4 v[68:69], off
	s_mov_b32 m0, s5
	v_lshl_add_u64 v[68:69], v[188:189], 0, s[18:19]
	v_add_f32_e32 v194, v214, v2
	s_add_i32 s4, s7, s38
	s_mov_b32 s5, m0
	s_mov_b32 m0, s4
	s_nop 0
	global_load_lds_dwordx4 v[68:69], off
	s_mov_b32 m0, s5
	v_max_f32_e32 v2, v53, v53
	v_max_f32_e32 v68, v52, v52
	v_max_f32_e32 v2, v68, v2
	v_max3_f32 v68, v54, v55, v37
	v_max3_f32 v2, v2, v36, v38
	v_max3_f32 v2, v2, v39, v56
	v_max3_f32 v68, v68, v58, v59
	v_max3_f32 v2, v2, v57, v40
	v_max3_f32 v68, v68, v42, v43
	v_max3_f32 v2, v2, v41, v60
	v_max3_f32 v68, v68, v62, v63
	v_max3_f32 v2, v2, v61, v44
	v_max3_f32 v68, v68, v46, v47
	v_max3_f32 v2, v2, v45, v64
	v_max3_f32 v68, v68, v66, v67
	v_max3_f32 v2, v2, v65, v48
	v_max3_f32 v68, v68, v50, v51
	v_max3_f32 v2, v2, v49, v68
	v_mov_b32_e32 v68, v2
	s_nop 1
	v_permlane32_swap_b32_e32 v2, v68
	v_max_f32_e32 v68, v68, v68
	v_max_f32_e32 v2, v2, v2
	v_max_f32_e32 v2, v2, v68
	v_sub_f32_e32 v2, v2, v210
	v_cmp_lt_f32_e32 vcc, s66, v2
	s_cmp_lg_u64 vcc, 0
	s_cselect_b64 s[22:23], -1, 0
	s_cbranch_vccz .LBB0_1984
	v_max_f32_e32 v2, v2, v2
	v_max_f32_e32 v68, 0, v2
	v_exp_f32_e64 v2, -v68
	s_and_saveexec_b64 s[4:5], s[0:1]
	ds_write_b32 v207, v2 offset:49152
	s_or_b64 exec, exec, s[4:5]
	v_add_f32_e32 v210, v210, v68
	v_mul_f32_e32 v194, v194, v2

.LBB0_1986:
	s_add_i32 s4, s7, 0x2000
	s_cmpk_lg_i32 s7, 0x4000
	s_cselect_b32 s58, s4, 0
	v_add_u32_e32 v166, s27, v209
	ds_read_b64_tr_b16 v[184:185], v166 offset:24576
	ds_read_b64_tr_b16 v[186:187], v166 offset:25088
	s_waitcnt lgkmcnt(9)
	v_mfma_f32_32x32x16_bf16 v[84:99], v[160:163], v[128:131], v[84:99]
	v_add_f32_e32 v100, v52, v53
	v_add_f32_e32 v100, v54, v100
	v_add_f32_e32 v100, v55, v100
	v_add_f32_e32 v100, v56, v100
	v_add_f32_e32 v100, v57, v100
	v_cvt_pk_bf16_f32 v120, v52, v53
	v_cvt_pk_bf16_f32 v121, v54, v55
	ds_read_b64_tr_b16 v[160:161], v166 offset:28672
	ds_read_b64_tr_b16 v[162:163], v166 offset:29184
	s_waitcnt lgkmcnt(10)
	v_mfma_f32_32x32x16_bf16 v[68:83], v[152:155], v[128:131], v[68:83]
	v_add_f32_e32 v52, v58, v100
	v_add_f32_e32 v52, v59, v52
	v_add_f32_e32 v52, v60, v52
	v_add_f32_e32 v52, v61, v52
	v_cvt_pk_bf16_f32 v122, v56, v57
	v_cvt_pk_bf16_f32 v123, v58, v59
	ds_read_b64_tr_b16 v[152:153], v166 offset:25600
	ds_read_b64_tr_b16 v[154:155], v166 offset:26112
	s_waitcnt lgkmcnt(11)
	v_mfma_f32_32x32x16_bf16 v[84:99], v[156:159], v[124:127], v[84:99]
	v_add_f32_e32 v52, v62, v52
	v_add_f32_e32 v52, v63, v52
	v_add_f32_e32 v52, v64, v52
	v_add_f32_e32 v52, v65, v52
	v_cvt_pk_bf16_f32 v112, v60, v61
	v_cvt_pk_bf16_f32 v113, v62, v63
	ds_read_b64_tr_b16 v[180:181], v166 offset:29696
	ds_read_b64_tr_b16 v[182:183], v166 offset:30208
	s_waitcnt lgkmcnt(12)
	v_mfma_f32_32x32x16_bf16 v[68:83], v[144:147], v[124:127], v[68:83]
	v_add_f32_e32 v52, v66, v52
	v_add_f32_e32 v52, v67, v52
	v_add_f32_e32 v52, v36, v52
	v_add_f32_e32 v52, v37, v52
	v_cvt_pk_bf16_f32 v114, v64, v65
	v_cvt_pk_bf16_f32 v115, v66, v67
	ds_read_b64_tr_b16 v[176:177], v166 offset:26624
	ds_read_b64_tr_b16 v[178:179], v166 offset:27136
	s_waitcnt lgkmcnt(13)
	v_mfma_f32_32x32x16_bf16 v[84:99], v[148:151], v[116:119], v[84:99]
	v_add_f32_e32 v52, v38, v52
	v_add_f32_e32 v52, v39, v52
	v_add_f32_e32 v52, v40, v52
	v_add_f32_e32 v52, v41, v52
	v_cvt_pk_bf16_f32 v104, v36, v37
	v_cvt_pk_bf16_f32 v105, v38, v39
	ds_read_b64_tr_b16 v[172:173], v166 offset:30720
	ds_read_b64_tr_b16 v[174:175], v166 offset:31232
	s_waitcnt lgkmcnt(14)
	v_mfma_f32_32x32x16_bf16 v[68:83], v[136:139], v[116:119], v[68:83]
	v_add_f32_e32 v36, v42, v52
	v_add_f32_e32 v36, v43, v36
	v_add_f32_e32 v36, v44, v36
	v_add_f32_e32 v36, v45, v36
	v_cvt_pk_bf16_f32 v106, v40, v41
	v_cvt_pk_bf16_f32 v107, v42, v43
	ds_read_b64_tr_b16 v[168:169], v166 offset:27648
	ds_read_b64_tr_b16 v[170:171], v166 offset:28160
	s_waitcnt lgkmcnt(14)
	v_mfma_f32_32x32x16_bf16 v[84:99], v[140:143], v[108:111], v[84:99]
	v_add_f32_e32 v36, v46, v36
	v_add_f32_e32 v36, v47, v36
	v_add_f32_e32 v36, v48, v36
	v_add_f32_e32 v36, v49, v36
	v_cvt_pk_bf16_f32 v100, v44, v45
	v_cvt_pk_bf16_f32 v101, v46, v47
	ds_read_b64_tr_b16 v[164:165], v166 offset:31744
	ds_read_b64_tr_b16 v[166:167], v166 offset:32256
	v_mfma_f32_32x32x16_bf16 v[68:83], v[132:135], v[108:111], v[68:83]
	v_add_f32_e32 v36, v50, v36
	v_add_f32_e32 v36, v51, v36
	v_add_f32_e32 v36, 0, v36
	v_cvt_pk_bf16_f32 v102, v48, v49
	v_cvt_pk_bf16_f32 v103, v50, v51
	s_nop 0
	v_add_f32_e32 v214, v194, v36
	v_max_f32_e32 v36, v85, v85
	v_max_f32_e32 v37, v84, v84
	v_max_f32_e32 v36, v37, v36
	s_nop 2
	v_max3_f32 v37, v86, v87, v69
	v_max3_f32 v36, v36, v68, v70
	v_max3_f32 v36, v36, v71, v88
	v_max3_f32 v37, v37, v90, v91
	v_max3_f32 v36, v36, v89, v72
	v_max3_f32 v37, v37, v74, v75
	v_max3_f32 v36, v36, v73, v92
	v_max3_f32 v37, v37, v94, v95
	v_max3_f32 v36, v36, v93, v76
	v_max3_f32 v37, v37, v78, v79
	v_max3_f32 v36, v36, v77, v96
	v_max3_f32 v37, v37, v98, v99
	v_max3_f32 v36, v36, v97, v80
	v_max3_f32 v37, v37, v82, v83
	v_max3_f32 v36, v36, v81, v37
	v_mov_b32_e32 v37, v36
	s_nop 1
	v_permlane32_swap_b32_e32 v36, v37
	v_max_f32_e32 v37, v37, v37
	v_max_f32_e32 v36, v36, v36
	v_max_f32_e32 v36, v36, v37
	s_add_i32 s4, s7, s37
	s_mov_b32 s5, m0
	s_mov_b32 m0, s4
	s_nop 0
	global_load_lds_dwordx4 v[190:191], off
	s_mov_b32 m0, s5
	v_sub_f32_e32 v36, v36, v210
	s_add_i32 s4, s58, s38
	s_mov_b32 s5, m0
	s_mov_b32 m0, s4
	s_nop 0
	global_load_lds_dwordx4 v[188:189], off
	s_mov_b32 m0, s5
	v_cmp_lt_f32_e32 vcc, s66, v36
	s_cmp_lg_u64 vcc, 0
	s_cselect_b64 s[22:23], -1, 0
	s_cbranch_vccz .LBB0_1990
	v_max_f32_e32 v36, v36, v36
	v_max_f32_e32 v37, 0, v36
	v_exp_f32_e64 v36, -v37
	s_and_saveexec_b64 s[4:5], s[0:1]
	ds_write_b32 v207, v36 offset:49152
	s_or_b64 exec, exec, s[4:5]
	v_add_f32_e32 v210, v210, v37
	v_mul_f32_e32 v214, v214, v36

.LBB0_1998:
	v_add_u32_e32 v166, s7, v209
	ds_read_b64_tr_b16 v[188:189], v166 offset:24576
	ds_read_b64_tr_b16 v[190:191], v166 offset:25088
	s_waitcnt lgkmcnt(9)
	v_mfma_f32_32x32x16_bf16 v[52:67], v[160:163], v[128:131], v[52:67]
	v_add_f32_e32 v100, v84, v85
	v_add_f32_e32 v100, v86, v100
	v_add_f32_e32 v100, v87, v100
	v_add_f32_e32 v100, v88, v100
	v_add_f32_e32 v100, v89, v100
	v_cvt_pk_bf16_f32 v120, v84, v85
	v_cvt_pk_bf16_f32 v121, v86, v87
	ds_read_b64_tr_b16 v[160:161], v166 offset:28672
	ds_read_b64_tr_b16 v[162:163], v166 offset:29184
	s_waitcnt lgkmcnt(10)
	v_mfma_f32_32x32x16_bf16 v[36:51], v[156:159], v[128:131], v[36:51]
	v_add_f32_e32 v84, v90, v100
	v_add_f32_e32 v84, v91, v84
	v_add_f32_e32 v84, v92, v84
	v_add_f32_e32 v84, v93, v84
	v_cvt_pk_bf16_f32 v122, v88, v89
	v_cvt_pk_bf16_f32 v123, v90, v91
	ds_read_b64_tr_b16 v[184:185], v166 offset:25600
	ds_read_b64_tr_b16 v[186:187], v166 offset:26112
	s_waitcnt lgkmcnt(11)
	v_mfma_f32_32x32x16_bf16 v[52:67], v[152:155], v[124:127], v[52:67]
	v_add_f32_e32 v84, v94, v84
	v_add_f32_e32 v84, v95, v84
	v_add_f32_e32 v84, v96, v84
	v_add_f32_e32 v84, v97, v84
	v_cvt_pk_bf16_f32 v112, v92, v93
	v_cvt_pk_bf16_f32 v113, v94, v95
	ds_read_b64_tr_b16 v[180:181], v166 offset:29696
	ds_read_b64_tr_b16 v[182:183], v166 offset:30208
	s_waitcnt lgkmcnt(12)
	v_mfma_f32_32x32x16_bf16 v[36:51], v[148:151], v[124:127], v[36:51]
	v_add_f32_e32 v84, v98, v84
	v_add_f32_e32 v84, v99, v84
	v_add_f32_e32 v84, v68, v84
	v_add_f32_e32 v84, v69, v84
	v_cvt_pk_bf16_f32 v114, v96, v97
	v_cvt_pk_bf16_f32 v115, v98, v99
	ds_read_b64_tr_b16 v[176:177], v166 offset:26624
	ds_read_b64_tr_b16 v[178:179], v166 offset:27136
	s_waitcnt lgkmcnt(13)
	v_mfma_f32_32x32x16_bf16 v[52:67], v[144:147], v[116:119], v[52:67]
	v_add_f32_e32 v84, v70, v84
	v_add_f32_e32 v84, v71, v84
	v_add_f32_e32 v84, v72, v84
	v_add_f32_e32 v84, v73, v84
	v_cvt_pk_bf16_f32 v104, v68, v69
	v_cvt_pk_bf16_f32 v105, v70, v71
	ds_read_b64_tr_b16 v[172:173], v166 offset:30720
	ds_read_b64_tr_b16 v[174:175], v166 offset:31232
	s_waitcnt lgkmcnt(14)
	v_mfma_f32_32x32x16_bf16 v[36:51], v[140:143], v[116:119], v[36:51]
	v_add_f32_e32 v68, v74, v84
	v_add_f32_e32 v68, v75, v68
	v_add_f32_e32 v68, v76, v68
	v_add_f32_e32 v68, v77, v68
	v_cvt_pk_bf16_f32 v106, v72, v73
	v_cvt_pk_bf16_f32 v107, v74, v75
	ds_read_b64_tr_b16 v[168:169], v166 offset:27648
	ds_read_b64_tr_b16 v[170:171], v166 offset:28160
	s_waitcnt lgkmcnt(14)
	v_mfma_f32_32x32x16_bf16 v[52:67], v[136:139], v[108:111], v[52:67]
	v_add_f32_e32 v68, v78, v68
	v_add_f32_e32 v68, v79, v68
	v_add_f32_e32 v68, v80, v68
	v_add_f32_e32 v68, v81, v68
	v_cvt_pk_bf16_f32 v100, v76, v77
	v_cvt_pk_bf16_f32 v101, v78, v79
	ds_read_b64_tr_b16 v[164:165], v166 offset:31744
	ds_read_b64_tr_b16 v[166:167], v166 offset:32256
	v_mfma_f32_32x32x16_bf16 v[36:51], v[132:135], v[108:111], v[36:51]
	v_add_f32_e32 v68, v82, v68
	v_add_f32_e32 v68, v83, v68
	v_add_f32_e32 v68, 0, v68
	v_cvt_pk_bf16_f32 v102, v80, v81
	v_cvt_pk_bf16_f32 v103, v82, v83
	s_add_i32 s8, s6, 1
	s_cmp_ge_u32 s8, s36
	s_cselect_b64 s[22:23], -1, 0
	s_and_b64 vcc, exec, s[22:23]
	s_cbranch_vccnz .LBB0_2000
	s_lshl_b64 s[4:5], s[8:9], 16
	s_add_i32 s7, s58, s37
	v_lshl_add_u64 v[70:71], v[196:197], 0, s[4:5]
	s_mov_b32 s4, m0
	s_mov_b32 m0, s7
	s_nop 0
	global_load_lds_dwordx4 v[70:71], off
	s_mov_b32 m0, s4

.LBB0_2012:
	v_add_u32_e32 v166, s58, v209
	ds_read_b64_tr_b16 v[188:189], v166 offset:24576
	ds_read_b64_tr_b16 v[190:191], v166 offset:25088
	s_waitcnt lgkmcnt(9)
	v_mfma_f32_32x32x16_bf16 v[84:99], v[160:163], v[128:131], v[84:99]
	v_add_f32_e32 v100, v52, v53
	v_add_f32_e32 v100, v54, v100
	v_add_f32_e32 v100, v55, v100
	v_add_f32_e32 v100, v56, v100
	v_add_f32_e32 v100, v57, v100
	v_cvt_pk_bf16_f32 v120, v52, v53
	v_cvt_pk_bf16_f32 v121, v54, v55
	ds_read_b64_tr_b16 v[192:193], v166 offset:28672
	ds_read_b64_tr_b16 v[194:195], v166 offset:29184
	s_waitcnt lgkmcnt(10)
	v_mfma_f32_32x32x16_bf16 v[68:83], v[156:159], v[128:131], v[68:83]
	v_add_f32_e32 v100, v58, v100
	v_add_f32_e32 v100, v59, v100
	v_add_f32_e32 v100, v60, v100
	v_add_f32_e32 v100, v61, v100
	v_cvt_pk_bf16_f32 v122, v56, v57
	v_cvt_pk_bf16_f32 v123, v58, v59
	ds_read_b64_tr_b16 v[184:185], v166 offset:25600
	ds_read_b64_tr_b16 v[186:187], v166 offset:26112
	s_waitcnt lgkmcnt(11)
	v_mfma_f32_32x32x16_bf16 v[84:99], v[152:155], v[124:127], v[84:99]
	v_add_f32_e32 v100, v62, v100
	v_add_f32_e32 v100, v63, v100
	v_add_f32_e32 v100, v64, v100
	v_add_f32_e32 v100, v65, v100
	v_cvt_pk_bf16_f32 v112, v60, v61
	v_cvt_pk_bf16_f32 v113, v62, v63
	ds_read_b64_tr_b16 v[180:181], v166 offset:29696
	ds_read_b64_tr_b16 v[182:183], v166 offset:30208
	s_waitcnt lgkmcnt(12)
	v_mfma_f32_32x32x16_bf16 v[68:83], v[148:151], v[124:127], v[68:83]
	v_add_f32_e32 v100, v66, v100
	v_add_f32_e32 v100, v67, v100
	v_add_f32_e32 v100, v36, v100
	v_add_f32_e32 v100, v37, v100
	v_cvt_pk_bf16_f32 v114, v64, v65
	v_cvt_pk_bf16_f32 v115, v66, v67
	ds_read_b64_tr_b16 v[176:177], v166 offset:26624
	ds_read_b64_tr_b16 v[178:179], v166 offset:27136
	s_waitcnt lgkmcnt(13)
	v_mfma_f32_32x32x16_bf16 v[84:99], v[144:147], v[116:119], v[84:99]
	v_add_f32_e32 v100, v38, v100
	v_add_f32_e32 v100, v39, v100
	v_add_f32_e32 v100, v40, v100
	v_add_f32_e32 v100, v41, v100
	v_cvt_pk_bf16_f32 v104, v36, v37
	v_cvt_pk_bf16_f32 v105, v38, v39
	ds_read_b64_tr_b16 v[172:173], v166 offset:30720
	ds_read_b64_tr_b16 v[174:175], v166 offset:31232
	s_waitcnt lgkmcnt(14)
	v_mfma_f32_32x32x16_bf16 v[68:83], v[140:143], v[116:119], v[68:83]
	v_add_f32_e32 v100, v42, v100
	v_add_f32_e32 v100, v43, v100
	v_add_f32_e32 v100, v44, v100
	v_add_f32_e32 v100, v45, v100
	v_cvt_pk_bf16_f32 v106, v40, v41
	v_cvt_pk_bf16_f32 v107, v42, v43
	ds_read_b64_tr_b16 v[168:169], v166 offset:27648
	ds_read_b64_tr_b16 v[170:171], v166 offset:28160
	s_waitcnt lgkmcnt(14)
	v_mfma_f32_32x32x16_bf16 v[84:99], v[136:139], v[108:111], v[84:99]
	v_add_f32_e32 v100, v46, v100
	v_add_f32_e32 v100, v47, v100
	v_add_f32_e32 v100, v48, v100
	v_add_f32_e32 v216, v49, v100
	v_cvt_pk_bf16_f32 v100, v44, v45
	v_cvt_pk_bf16_f32 v101, v46, v47
	ds_read_b64_tr_b16 v[164:165], v166 offset:31744
	ds_read_b64_tr_b16 v[166:167], v166 offset:32256
	v_mfma_f32_32x32x16_bf16 v[68:83], v[132:135], v[108:111], v[68:83]
	v_add_f32_e32 v102, v50, v216
	v_add_f32_e32 v102, v51, v102
	v_add_f32_e32 v216, 0, v102
	v_cvt_pk_bf16_f32 v102, v48, v49
	v_cvt_pk_bf16_f32 v103, v50, v51
	s_add_i32 s8, s6, 2
	s_cmp_ge_u32 s8, s36
	s_cselect_b64 s[26:27], -1, 0
	s_and_b64 vcc, exec, s[26:27]
	s_cbranch_vccnz .LBB0_2014
	s_lshl_b64 s[4:5], s[8:9], 16
	s_add_i32 s7, s59, s37
	v_lshl_add_u64 v[218:219], v[196:197], 0, s[4:5]
	s_mov_b32 s4, m0
	s_mov_b32 m0, s7
	s_nop 0
	global_load_lds_dwordx4 v[218:219], off
	s_mov_b32 m0, s4

.LBB0_2045:
	v_add_u32_e32 v168, s59, v209
	ds_read_b64_tr_b16 v[164:165], v168 offset:24576
	ds_read_b64_tr_b16 v[166:167], v168 offset:25088
	s_waitcnt lgkmcnt(9)
	v_mfma_f32_32x32x16_bf16 v[52:67], v[160:163], v[128:131], v[52:67]
	v_add_f32_e32 v100, v84, v85
	v_add_f32_e32 v100, v86, v100
	v_add_f32_e32 v100, v87, v100
	v_add_f32_e32 v100, v88, v100
	v_add_f32_e32 v100, v89, v100
	v_cvt_pk_bf16_f32 v120, v84, v85
	v_cvt_pk_bf16_f32 v121, v86, v87
	ds_read_b64_tr_b16 v[160:161], v168 offset:28672
	ds_read_b64_tr_b16 v[162:163], v168 offset:29184
	s_waitcnt lgkmcnt(10)
	v_mfma_f32_32x32x16_bf16 v[36:51], v[156:159], v[128:131], v[36:51]
	v_add_f32_e32 v84, v90, v100
	v_add_f32_e32 v84, v91, v84
	v_add_f32_e32 v84, v92, v84
	v_add_f32_e32 v84, v93, v84
	v_cvt_pk_bf16_f32 v122, v88, v89
	v_cvt_pk_bf16_f32 v123, v90, v91
	ds_read_b64_tr_b16 v[128:129], v168 offset:25600
	ds_read_b64_tr_b16 v[130:131], v168 offset:26112
	s_waitcnt lgkmcnt(11)
	v_mfma_f32_32x32x16_bf16 v[52:67], v[152:155], v[124:127], v[52:67]
	v_add_f32_e32 v84, v94, v84
	v_add_f32_e32 v84, v95, v84
	v_add_f32_e32 v84, v96, v84
	v_add_f32_e32 v84, v97, v84
	v_cvt_pk_bf16_f32 v112, v92, v93
	v_cvt_pk_bf16_f32 v113, v94, v95
	ds_read_b64_tr_b16 v[92:93], v168 offset:29696
	ds_read_b64_tr_b16 v[94:95], v168 offset:30208
	s_waitcnt lgkmcnt(12)
	v_mfma_f32_32x32x16_bf16 v[36:51], v[148:151], v[124:127], v[36:51]
	v_add_f32_e32 v84, v98, v84
	v_add_f32_e32 v84, v99, v84
	v_add_f32_e32 v84, v68, v84
	v_add_f32_e32 v84, v69, v84
	v_cvt_pk_bf16_f32 v114, v96, v97
	v_cvt_pk_bf16_f32 v115, v98, v99
	ds_read_b64_tr_b16 v[88:89], v168 offset:26624
	ds_read_b64_tr_b16 v[90:91], v168 offset:27136
	s_waitcnt lgkmcnt(13)
	v_mfma_f32_32x32x16_bf16 v[52:67], v[144:147], v[116:119], v[52:67]
	v_add_f32_e32 v84, v70, v84
	v_add_f32_e32 v84, v71, v84
	v_add_f32_e32 v84, v72, v84
	v_add_f32_e32 v96, v73, v84
	v_cvt_pk_bf16_f32 v104, v68, v69
	v_cvt_pk_bf16_f32 v105, v70, v71
	ds_read_b64_tr_b16 v[84:85], v168 offset:30720
	ds_read_b64_tr_b16 v[86:87], v168 offset:31232
	s_waitcnt lgkmcnt(14)
	v_mfma_f32_32x32x16_bf16 v[36:51], v[140:143], v[116:119], v[36:51]
	v_add_f32_e32 v68, v74, v96
	v_add_f32_e32 v68, v75, v68
	v_add_f32_e32 v68, v76, v68
	v_add_f32_e32 v68, v77, v68
	v_cvt_pk_bf16_f32 v106, v72, v73
	v_cvt_pk_bf16_f32 v107, v74, v75
	ds_read_b64_tr_b16 v[72:73], v168 offset:27648
	ds_read_b64_tr_b16 v[74:75], v168 offset:28160
	s_waitcnt lgkmcnt(14)
	v_mfma_f32_32x32x16_bf16 v[52:67], v[136:139], v[108:111], v[52:67]
	v_add_f32_e32 v68, v78, v68
	v_add_f32_e32 v68, v79, v68
	v_add_f32_e32 v68, v80, v68
	v_add_f32_e32 v96, v81, v68
	v_cvt_pk_bf16_f32 v100, v76, v77
	v_cvt_pk_bf16_f32 v101, v78, v79
	ds_read_b64_tr_b16 v[68:69], v168 offset:31744
	ds_read_b64_tr_b16 v[70:71], v168 offset:32256
	v_mfma_f32_32x32x16_bf16 v[36:51], v[132:135], v[108:111], v[36:51]
	v_add_f32_e32 v76, v82, v96
	v_add_f32_e32 v76, v83, v76
	v_add_f32_e32 v76, 0, v76
	v_cvt_pk_bf16_f32 v102, v80, v81
	v_cvt_pk_bf16_f32 v103, v82, v83
	v_or_b32_e32 v78, 0xe0, v208
	v_or_b32_e32 v77, 0xc0, v208
	v_cmp_le_i32_e32 vcc, v78, v215
	v_add_f32_e32 v76, v214, v76
	s_nop 3
	v_cndmask_b32_e32 v36, v199, v36, vcc
	v_cmp_lt_i32_e32 vcc, v77, v215
	s_nop 1
	v_cndmask_b32_e32 v53, v199, v53, vcc
	v_cmp_le_i32_e32 vcc, v77, v215
	v_or_b32_e32 v77, 0xe1, v208
	s_nop 0
	v_cndmask_b32_e32 v52, v199, v52, vcc
	v_cmp_le_i32_e32 vcc, v77, v215
	v_or_b32_e32 v77, 0xc2, v208
	v_max_f32_e32 v78, v52, v52
	v_cndmask_b32_e32 v37, v199, v37, vcc
	v_cmp_le_i32_e32 vcc, v77, v215
	v_or_b32_e32 v77, 0xe2, v208
	s_nop 0
	v_cndmask_b32_e32 v54, v199, v54, vcc
	v_cmp_le_i32_e32 vcc, v77, v215
	v_or_b32_e32 v77, 0xc3, v208
	s_nop 0
	v_cndmask_b32_e32 v38, v199, v38, vcc
	v_cmp_le_i32_e32 vcc, v77, v215
	v_or_b32_e32 v77, 0xe3, v208
	s_nop 0
	v_cndmask_b32_e32 v55, v199, v55, vcc
	v_cmp_le_i32_e32 vcc, v77, v215
	v_or_b32_e32 v77, 0xc8, v208
	s_nop 0
	v_cndmask_b32_e32 v39, v199, v39, vcc
	v_cmp_le_i32_e32 vcc, v77, v215
	v_or_b32_e32 v77, 0xe8, v208
	s_nop 0
	v_cndmask_b32_e32 v56, v199, v56, vcc
	v_cmp_le_i32_e32 vcc, v77, v215
	v_or_b32_e32 v77, 0xc9, v208
	s_nop 0
	v_cndmask_b32_e32 v40, v199, v40, vcc
	v_cmp_le_i32_e32 vcc, v77, v215
	v_or_b32_e32 v77, 0xe9, v208
	s_nop 0
	v_cndmask_b32_e32 v57, v199, v57, vcc
	v_cmp_le_i32_e32 vcc, v77, v215
	v_or_b32_e32 v77, 0xca, v208
	s_nop 0
	v_cndmask_b32_e32 v41, v199, v41, vcc
	v_cmp_le_i32_e32 vcc, v77, v215
	v_or_b32_e32 v77, 0xea, v208
	s_nop 0
	v_cndmask_b32_e32 v58, v199, v58, vcc
	v_cmp_le_i32_e32 vcc, v77, v215
	v_or_b32_e32 v77, 0xcb, v208
	s_nop 0
	v_cndmask_b32_e32 v42, v199, v42, vcc
	v_cmp_le_i32_e32 vcc, v77, v215
	v_or_b32_e32 v77, 0xeb, v208
	s_nop 0
	v_cndmask_b32_e32 v59, v199, v59, vcc
	v_cmp_le_i32_e32 vcc, v77, v215
	v_or_b32_e32 v77, 0xd0, v208
	s_nop 0
	v_cndmask_b32_e32 v43, v199, v43, vcc
	v_cmp_le_i32_e32 vcc, v77, v215
	v_or_b32_e32 v77, 0xf0, v208
	s_nop 0
	v_cndmask_b32_e32 v60, v199, v60, vcc
	v_cmp_le_i32_e32 vcc, v77, v215
	v_or_b32_e32 v77, 0xd1, v208
	s_nop 0
	v_cndmask_b32_e32 v44, v199, v44, vcc
	v_cmp_le_i32_e32 vcc, v77, v215
	v_or_b32_e32 v77, 0xf1, v208
	s_nop 0
	v_cndmask_b32_e32 v61, v199, v61, vcc
	v_cmp_le_i32_e32 vcc, v77, v215
	v_or_b32_e32 v77, 0xd2, v208
	s_nop 0
	v_cndmask_b32_e32 v45, v199, v45, vcc
	v_cmp_le_i32_e32 vcc, v77, v215
	v_or_b32_e32 v77, 0xf2, v208
	s_nop 0
	v_cndmask_b32_e32 v62, v199, v62, vcc
	v_cmp_le_i32_e32 vcc, v77, v215
	v_or_b32_e32 v77, 0xd3, v208
	s_nop 0
	v_cndmask_b32_e32 v46, v199, v46, vcc
	v_cmp_le_i32_e32 vcc, v77, v215
	v_or_b32_e32 v77, 0xf3, v208
	s_nop 0
	v_cndmask_b32_e32 v63, v199, v63, vcc
	v_cmp_le_i32_e32 vcc, v77, v215
	v_or_b32_e32 v77, 0xd8, v208
	s_nop 0
	v_cndmask_b32_e32 v47, v199, v47, vcc
	v_cmp_le_i32_e32 vcc, v77, v215
	v_or_b32_e32 v77, 0xf8, v208
	s_nop 0
	v_cndmask_b32_e32 v64, v199, v64, vcc
	v_cmp_le_i32_e32 vcc, v77, v215
	v_or_b32_e32 v77, 0xd9, v208
	s_nop 0
	v_cndmask_b32_e32 v48, v199, v48, vcc
	v_cmp_le_i32_e32 vcc, v77, v215
	v_or_b32_e32 v77, 0xf9, v208
	s_nop 0
	v_cndmask_b32_e32 v65, v199, v65, vcc
	v_cmp_le_i32_e32 vcc, v77, v215
	v_or_b32_e32 v77, 0xda, v208
	s_nop 0
	v_cndmask_b32_e32 v49, v199, v49, vcc
	v_cmp_le_i32_e32 vcc, v77, v215
	v_or_b32_e32 v77, 0xfa, v208
	s_nop 0
	v_cndmask_b32_e32 v66, v199, v66, vcc
	v_cmp_le_i32_e32 vcc, v77, v215
	v_or_b32_e32 v77, 0xdb, v208
	s_nop 0
	v_cndmask_b32_e32 v50, v199, v50, vcc
	v_cmp_le_i32_e32 vcc, v77, v215
	v_or_b32_e32 v77, 0xfb, v208
	s_nop 0
	v_cndmask_b32_e32 v67, v199, v67, vcc
	v_cmp_le_i32_e32 vcc, v77, v215
	v_max_f32_e32 v77, v53, v53
	v_max_f32_e32 v77, v78, v77
	v_max3_f32 v78, v54, v55, v37
	v_max3_f32 v77, v77, v36, v38
	v_max3_f32 v77, v77, v39, v56
	v_max3_f32 v78, v78, v58, v59
	v_max3_f32 v77, v77, v57, v40
	v_max3_f32 v78, v78, v42, v43
	v_max3_f32 v77, v77, v41, v60
	v_max3_f32 v78, v78, v62, v63
	v_max3_f32 v77, v77, v61, v44
	v_max3_f32 v78, v78, v46, v47
	v_cndmask_b32_e32 v51, v199, v51, vcc
	v_max3_f32 v77, v77, v45, v64
	v_max3_f32 v78, v78, v66, v67
	v_max3_f32 v77, v77, v65, v48
	v_max3_f32 v78, v78, v50, v51
	v_max3_f32 v77, v77, v49, v78
	v_mov_b32_e32 v78, v77
	s_nop 1
	v_permlane32_swap_b32_e32 v77, v78
	v_max_f32_e32 v78, v78, v78
	v_max_f32_e32 v77, v77, v77
	v_max_f32_e32 v77, v77, v78
	v_sub_f32_e32 v77, v77, v210
	v_cmp_lt_f32_e32 vcc, s66, v77
	s_cmp_lg_u64 vcc, 0
	s_cselect_b64 s[6:7], -1, 0
	s_cbranch_vccz .LBB0_2049
	v_max_f32_e32 v77, v77, v77
	v_max_f32_e32 v78, 0, v77
	v_exp_f32_e64 v77, -v78
	s_and_saveexec_b64 s[4:5], s[0:1]
	ds_write_b32 v207, v77 offset:49152
	s_or_b64 exec, exec, s[4:5]
	v_add_f32_e32 v210, v210, v78
	v_mul_f32_e32 v76, v76, v77
